# v48 + first DMA wait after an epilogue relaxed to vmcnt(24) (seam no longer waits for the epilogue's store acks before the first barrier)
# speedup vs baseline: 1.0222x; 1.0135x over previous
.LBB0_261:
	s_ashr_i32 s35, s34, 31
	s_lshl_b64 vcc, s[34:35], 21
	s_add_u32 s13, s30, vcc_lo
	s_addc_u32 s15, s31, vcc_hi
	s_add_u32 s54, s13, s54
	s_addc_u32 s55, s15, s55
	s_and_b64 s[86:87], s[86:87], exec
	s_cselect_b32 s13, s55, s11
	s_cselect_b32 s15, s54, s10
	s_add_i32 s35, s19, -2
	s_add_u32 s40, s10, 0x100
	s_addc_u32 s49, s11, 0
	s_add_u32 s10, s38, 0x100080
	s_addc_u32 s11, s39, 0
	s_mov_b32 s38, 0
	s_add_i32 vcc_lo, s38, 2
	s_add_u32 s39, s10, 0xfff00080
	s_addc_u32 s66, s11, -1
	s_add_i32 s67, 0, 0x10000
	s_cmp_eq_u32 s35, s38
	s_cselect_b32 s87, s53, s66
	s_cselect_b32 s86, s52, s39
	s_cselect_b32 s39, s13, s49
	s_cselect_b32 s38, s15, s40
	s_add_i32 vcc_hi, 0, 0x14000
	v_add_u32_e32 v142, s67, v1
	v_add_u32_e32 v180, vcc_hi, v1
	ds_read_b128 v[130:133], v142
	ds_read_b128 v[134:137], v142 offset:1024
	ds_read_b128 v[138:141], v142 offset:2048
	ds_read_b128 v[142:145], v142 offset:3072
	ds_read_b128 v[168:171], v180
	ds_read_b128 v[172:175], v180 offset:1024
	ds_read_b128 v[176:179], v180 offset:2048
	ds_read_b128 v[180:183], v180 offset:3072
	s_add_i32 m0, s85, 0xc000
	ds_read_b128 v[198:201], v197
	ds_read_b128 v[202:205], v197 offset:1024
	ds_read_b128 v[206:209], v197 offset:2048
	ds_read_b128 v[210:213], v197 offset:3072
	ds_read_b128 v[214:217], v197 offset:4096
	ds_read_b128 v[218:221], v197 offset:5120
	ds_read_b128 v[222:225], v197 offset:6144
	ds_read_b128 v[226:229], v197 offset:7168
	global_load_lds_dwordx4 v164, s[10:11]
	s_add_i32 m0, s85, 0xe000
	s_nop 0
	global_load_lds_dwordx4 v166, s[10:11]
	s_waitcnt vmcnt(24)
	s_waitcnt lgkmcnt(0)
	s_setprio 1
	s_barrier
	v_mfma_f32_16x16x32_bf16 v[114:117], v[130:133], v[198:201], 0
	v_mfma_f32_16x16x32_bf16 v[118:121], v[138:141], v[198:201], 0
	v_mfma_f32_16x16x32_bf16 v[102:105], v[130:133], v[206:209], 0
	v_mfma_f32_16x16x32_bf16 v[98:101], v[138:141], v[206:209], 0
	v_mfma_f32_16x16x32_bf16 v[86:89], v[130:133], v[214:217], 0
	v_mfma_f32_16x16x32_bf16 v[82:85], v[138:141], v[214:217], 0
	v_mfma_f32_16x16x32_bf16 v[54:57], v[130:133], v[222:225], 0
	v_mfma_f32_16x16x32_bf16 v[50:53], v[138:141], v[222:225], 0
	v_mfma_f32_16x16x32_bf16 v[114:117], v[134:137], v[202:205], v[114:117]
	v_mfma_f32_16x16x32_bf16 v[118:121], v[142:145], v[202:205], v[118:121]
	v_mfma_f32_16x16x32_bf16 v[102:105], v[134:137], v[210:213], v[102:105]
	v_mfma_f32_16x16x32_bf16 v[98:101], v[142:145], v[210:213], v[98:101]
	v_mfma_f32_16x16x32_bf16 v[86:89], v[134:137], v[218:221], v[86:89]
	v_mfma_f32_16x16x32_bf16 v[82:85], v[142:145], v[218:221], v[82:85]
	v_mfma_f32_16x16x32_bf16 v[54:57], v[134:137], v[226:229], v[54:57]
	v_mfma_f32_16x16x32_bf16 v[50:53], v[142:145], v[226:229], v[50:53]
	s_setprio 0
	s_setprio 1
	v_mfma_f32_16x16x32_bf16 v[126:129], v[168:171], v[198:201], 0
	v_mfma_f32_16x16x32_bf16 v[122:125], v[176:179], v[198:201], 0
	v_mfma_f32_16x16x32_bf16 v[110:113], v[168:171], v[206:209], 0
	v_mfma_f32_16x16x32_bf16 v[106:109], v[176:179], v[206:209], 0
	v_mfma_f32_16x16x32_bf16 v[94:97], v[168:171], v[214:217], 0
	v_mfma_f32_16x16x32_bf16 v[90:93], v[176:179], v[214:217], 0
	v_mfma_f32_16x16x32_bf16 v[70:73], v[168:171], v[222:225], 0
	v_mfma_f32_16x16x32_bf16 v[66:69], v[176:179], v[222:225], 0
	v_mfma_f32_16x16x32_bf16 v[126:129], v[172:175], v[202:205], v[126:129]
	v_mfma_f32_16x16x32_bf16 v[122:125], v[180:183], v[202:205], v[122:125]
	v_mfma_f32_16x16x32_bf16 v[110:113], v[172:175], v[210:213], v[110:113]
	v_mfma_f32_16x16x32_bf16 v[106:109], v[180:183], v[210:213], v[106:109]
	v_mfma_f32_16x16x32_bf16 v[94:97], v[172:175], v[218:221], v[94:97]
	v_mfma_f32_16x16x32_bf16 v[90:93], v[180:183], v[218:221], v[90:93]
	v_mfma_f32_16x16x32_bf16 v[70:73], v[172:175], v[226:229], v[70:73]
	v_mfma_f32_16x16x32_bf16 v[66:69], v[180:183], v[226:229], v[66:69]
	s_barrier
	s_setprio 0
	s_add_i32 s66, s67, s97
	s_add_u32 s98, s38, 0x80
	s_addc_u32 s99, s39, 0
	s_mov_b32 m0, s66
	ds_read_b128 v[198:201], v197 offset:16384
	ds_read_b128 v[202:205], v197 offset:17408
	ds_read_b128 v[206:209], v197 offset:18432
	ds_read_b128 v[210:213], v197 offset:19456
	ds_read_b128 v[214:217], v197 offset:20480
	ds_read_b128 v[218:221], v197 offset:21504
	ds_read_b128 v[222:225], v197 offset:22528
	ds_read_b128 v[226:229], v197 offset:23552
	global_load_lds_dwordx4 v156, s[38:39]
	s_add_i32 m0, s66, 0x2000
	s_add_u32 s66, s38, 0x100000
	s_addc_u32 s67, s39, 0
	s_add_i32 vcc_hi, vcc_hi, s97
	global_load_lds_dwordx4 v160, s[38:39]
	s_mov_b32 m0, vcc_hi
	s_add_u32 s100, s86, 0x80
	s_addc_u32 s101, s87, 0
	global_load_lds_dwordx4 v156, s[66:67]
	s_add_i32 m0, vcc_hi, 0x2000
	s_nop 0
	global_load_lds_dwordx4 v160, s[66:67]
	s_mov_b32 m0, s85
	s_nop 0
	global_load_lds_dwordx4 v154, s[86:87]
	s_mov_b32 m0, s92
	s_nop 0
	global_load_lds_dwordx4 v158, s[86:87]
	s_waitcnt vmcnt(8)
	s_waitcnt lgkmcnt(0)
	s_setprio 1
	s_barrier
	v_mfma_f32_16x16x32_bf16 v[62:65], v[130:133], v[198:201], 0
	v_mfma_f32_16x16x32_bf16 v[58:61], v[138:141], v[198:201], 0
	v_mfma_f32_16x16x32_bf16 v[38:41], v[130:133], v[206:209], 0
	v_mfma_f32_16x16x32_bf16 v[34:37], v[138:141], v[206:209], 0
	v_mfma_f32_16x16x32_bf16 v[22:25], v[130:133], v[214:217], 0
	v_mfma_f32_16x16x32_bf16 v[18:21], v[138:141], v[214:217], 0
	v_mfma_f32_16x16x32_bf16 v[6:9], v[130:133], v[222:225], 0
	v_mfma_f32_16x16x32_bf16 v[2:5], v[138:141], v[222:225], 0
	v_mfma_f32_16x16x32_bf16 v[62:65], v[134:137], v[202:205], v[62:65]
	v_mfma_f32_16x16x32_bf16 v[58:61], v[142:145], v[202:205], v[58:61]
	v_mfma_f32_16x16x32_bf16 v[38:41], v[134:137], v[210:213], v[38:41]
	v_mfma_f32_16x16x32_bf16 v[34:37], v[142:145], v[210:213], v[34:37]
	v_mfma_f32_16x16x32_bf16 v[22:25], v[134:137], v[218:221], v[22:25]
	v_mfma_f32_16x16x32_bf16 v[18:21], v[142:145], v[218:221], v[18:21]
	v_mfma_f32_16x16x32_bf16 v[6:9], v[134:137], v[226:229], v[6:9]
	v_mfma_f32_16x16x32_bf16 v[2:5], v[142:145], v[226:229], v[2:5]
	s_setprio 0
	s_setprio 1
	v_mfma_f32_16x16x32_bf16 v[78:81], v[168:171], v[198:201], 0
	v_mfma_f32_16x16x32_bf16 v[74:77], v[176:179], v[198:201], 0
	v_mfma_f32_16x16x32_bf16 v[46:49], v[168:171], v[206:209], 0
	v_mfma_f32_16x16x32_bf16 v[42:45], v[176:179], v[206:209], 0
	v_mfma_f32_16x16x32_bf16 v[30:33], v[168:171], v[214:217], 0
	v_mfma_f32_16x16x32_bf16 v[26:29], v[176:179], v[214:217], 0
	v_mfma_f32_16x16x32_bf16 v[14:17], v[168:171], v[222:225], 0
	v_mfma_f32_16x16x32_bf16 v[10:13], v[176:179], v[222:225], 0
	v_mfma_f32_16x16x32_bf16 v[78:81], v[172:175], v[202:205], v[78:81]
	v_mfma_f32_16x16x32_bf16 v[74:77], v[180:183], v[202:205], v[74:77]
	v_mfma_f32_16x16x32_bf16 v[46:49], v[172:175], v[210:213], v[46:49]
	v_mfma_f32_16x16x32_bf16 v[42:45], v[180:183], v[210:213], v[42:45]
	v_mfma_f32_16x16x32_bf16 v[30:33], v[172:175], v[218:221], v[30:33]
	v_mfma_f32_16x16x32_bf16 v[26:29], v[180:183], v[218:221], v[26:29]
	v_mfma_f32_16x16x32_bf16 v[14:17], v[172:175], v[226:229], v[14:17]
	v_mfma_f32_16x16x32_bf16 v[10:13], v[180:183], v[226:229], v[10:13]
	s_barrier
	s_setprio 0
	s_add_i32 vcc_hi, 0, 0x18000
	s_add_i32 s56, 0, 0x1c000
	v_add_u32_e32 v142, vcc_hi, v1
	v_add_u32_e32 v180, s56, v1
	ds_read_b128 v[130:133], v142
	ds_read_b128 v[134:137], v142 offset:1024
	ds_read_b128 v[138:141], v142 offset:2048
	ds_read_b128 v[142:145], v142 offset:3072
	ds_read_b128 v[168:171], v180
	ds_read_b128 v[172:175], v180 offset:1024
	ds_read_b128 v[176:179], v180 offset:2048
	ds_read_b128 v[180:183], v180 offset:3072
	s_add_u32 s66, s86, 0x100000
	s_addc_u32 s67, s87, 0
	s_mov_b32 m0, s93
	ds_read_b128 v[198:201], v197 offset:32768
	ds_read_b128 v[202:205], v197 offset:33792
	ds_read_b128 v[206:209], v197 offset:34816
	ds_read_b128 v[210:213], v197 offset:35840
	ds_read_b128 v[214:217], v197 offset:36864
	ds_read_b128 v[218:221], v197 offset:37888
	ds_read_b128 v[222:225], v197 offset:38912
	ds_read_b128 v[226:229], v197 offset:39936
	global_load_lds_dwordx4 v154, s[66:67]
	s_mov_b32 m0, s42
	s_nop 0
	global_load_lds_dwordx4 v158, s[66:67]
	s_waitcnt vmcnt(8)
	s_waitcnt lgkmcnt(0)
	s_setprio 1
	s_barrier
	v_mfma_f32_16x16x32_bf16 v[114:117], v[130:133], v[198:201], v[114:117]
	v_mfma_f32_16x16x32_bf16 v[118:121], v[138:141], v[198:201], v[118:121]
	v_mfma_f32_16x16x32_bf16 v[102:105], v[130:133], v[206:209], v[102:105]
	v_mfma_f32_16x16x32_bf16 v[98:101], v[138:141], v[206:209], v[98:101]
	v_mfma_f32_16x16x32_bf16 v[86:89], v[130:133], v[214:217], v[86:89]
	v_mfma_f32_16x16x32_bf16 v[82:85], v[138:141], v[214:217], v[82:85]
	v_mfma_f32_16x16x32_bf16 v[54:57], v[130:133], v[222:225], v[54:57]
	v_mfma_f32_16x16x32_bf16 v[50:53], v[138:141], v[222:225], v[50:53]
	v_mfma_f32_16x16x32_bf16 v[114:117], v[134:137], v[202:205], v[114:117]
	v_mfma_f32_16x16x32_bf16 v[118:121], v[142:145], v[202:205], v[118:121]
	v_mfma_f32_16x16x32_bf16 v[102:105], v[134:137], v[210:213], v[102:105]
	v_mfma_f32_16x16x32_bf16 v[98:101], v[142:145], v[210:213], v[98:101]
	v_mfma_f32_16x16x32_bf16 v[86:89], v[134:137], v[218:221], v[86:89]
	v_mfma_f32_16x16x32_bf16 v[82:85], v[142:145], v[218:221], v[82:85]
	v_mfma_f32_16x16x32_bf16 v[54:57], v[134:137], v[226:229], v[54:57]
	v_mfma_f32_16x16x32_bf16 v[50:53], v[142:145], v[226:229], v[50:53]
	s_setprio 0
	s_setprio 1
	v_mfma_f32_16x16x32_bf16 v[126:129], v[168:171], v[198:201], v[126:129]
	v_mfma_f32_16x16x32_bf16 v[122:125], v[176:179], v[198:201], v[122:125]
	v_mfma_f32_16x16x32_bf16 v[110:113], v[168:171], v[206:209], v[110:113]
	v_mfma_f32_16x16x32_bf16 v[106:109], v[176:179], v[206:209], v[106:109]
	v_mfma_f32_16x16x32_bf16 v[94:97], v[168:171], v[214:217], v[94:97]
	v_mfma_f32_16x16x32_bf16 v[90:93], v[176:179], v[214:217], v[90:93]
	v_mfma_f32_16x16x32_bf16 v[70:73], v[168:171], v[222:225], v[70:73]
	v_mfma_f32_16x16x32_bf16 v[66:69], v[176:179], v[222:225], v[66:69]
	v_mfma_f32_16x16x32_bf16 v[126:129], v[172:175], v[202:205], v[126:129]
	v_mfma_f32_16x16x32_bf16 v[122:125], v[180:183], v[202:205], v[122:125]
	v_mfma_f32_16x16x32_bf16 v[110:113], v[172:175], v[210:213], v[110:113]
	v_mfma_f32_16x16x32_bf16 v[106:109], v[180:183], v[210:213], v[106:109]
	v_mfma_f32_16x16x32_bf16 v[94:97], v[172:175], v[218:221], v[94:97]
	v_mfma_f32_16x16x32_bf16 v[90:93], v[180:183], v[218:221], v[90:93]
	v_mfma_f32_16x16x32_bf16 v[70:73], v[172:175], v[226:229], v[70:73]
	v_mfma_f32_16x16x32_bf16 v[66:69], v[180:183], v[226:229], v[66:69]
	s_barrier
	s_setprio 0
	s_add_i32 s57, vcc_hi, s97
	s_mov_b32 m0, s57
	ds_read_b128 v[198:201], v197 offset:49152
	ds_read_b128 v[202:205], v197 offset:50176
	ds_read_b128 v[206:209], v197 offset:51200
	ds_read_b128 v[210:213], v197 offset:52224
	ds_read_b128 v[214:217], v197 offset:53248
	ds_read_b128 v[218:221], v197 offset:54272
	ds_read_b128 v[222:225], v197 offset:55296
	ds_read_b128 v[226:229], v197 offset:56320
	global_load_lds_dwordx4 v156, s[98:99]
	s_add_i32 m0, s57, 0x2000
	s_add_u32 s38, s38, 0x100080
	s_addc_u32 s39, s39, 0
	s_add_i32 s56, s56, s97
	global_load_lds_dwordx4 v160, s[98:99]
	s_mov_b32 m0, s56
	s_nop 0
	global_load_lds_dwordx4 v156, s[38:39]
	s_add_i32 m0, s56, 0x2000
	s_nop 0
	global_load_lds_dwordx4 v160, s[38:39]
	s_mov_b32 m0, s43
	s_nop 0
	global_load_lds_dwordx4 v154, s[100:101]
	s_mov_b32 m0, s90
	s_nop 0
	global_load_lds_dwordx4 v158, s[100:101]
	s_waitcnt vmcnt(8)
	s_waitcnt lgkmcnt(0)
	s_setprio 1
	s_barrier
	v_mfma_f32_16x16x32_bf16 v[62:65], v[130:133], v[198:201], v[62:65]
	v_mfma_f32_16x16x32_bf16 v[58:61], v[138:141], v[198:201], v[58:61]
	v_mfma_f32_16x16x32_bf16 v[38:41], v[130:133], v[206:209], v[38:41]
	v_mfma_f32_16x16x32_bf16 v[34:37], v[138:141], v[206:209], v[34:37]
	v_mfma_f32_16x16x32_bf16 v[22:25], v[130:133], v[214:217], v[22:25]
	v_mfma_f32_16x16x32_bf16 v[18:21], v[138:141], v[214:217], v[18:21]
	v_mfma_f32_16x16x32_bf16 v[6:9], v[130:133], v[222:225], v[6:9]
	v_mfma_f32_16x16x32_bf16 v[2:5], v[138:141], v[222:225], v[2:5]
	v_mfma_f32_16x16x32_bf16 v[62:65], v[134:137], v[202:205], v[62:65]
	v_mfma_f32_16x16x32_bf16 v[58:61], v[142:145], v[202:205], v[58:61]
	v_mfma_f32_16x16x32_bf16 v[38:41], v[134:137], v[210:213], v[38:41]
	v_mfma_f32_16x16x32_bf16 v[34:37], v[142:145], v[210:213], v[34:37]
	v_mfma_f32_16x16x32_bf16 v[22:25], v[134:137], v[218:221], v[22:25]
	v_mfma_f32_16x16x32_bf16 v[18:21], v[142:145], v[218:221], v[18:21]
	v_mfma_f32_16x16x32_bf16 v[6:9], v[134:137], v[226:229], v[6:9]
	v_mfma_f32_16x16x32_bf16 v[2:5], v[142:145], v[226:229], v[2:5]
	s_setprio 0
	s_setprio 1
	v_mfma_f32_16x16x32_bf16 v[78:81], v[168:171], v[198:201], v[78:81]
	v_mfma_f32_16x16x32_bf16 v[74:77], v[176:179], v[198:201], v[74:77]
	v_mfma_f32_16x16x32_bf16 v[46:49], v[168:171], v[206:209], v[46:49]
	v_mfma_f32_16x16x32_bf16 v[42:45], v[176:179], v[206:209], v[42:45]
	v_mfma_f32_16x16x32_bf16 v[30:33], v[168:171], v[214:217], v[30:33]
	v_mfma_f32_16x16x32_bf16 v[26:29], v[176:179], v[214:217], v[26:29]
	v_mfma_f32_16x16x32_bf16 v[14:17], v[168:171], v[222:225], v[14:17]
	v_mfma_f32_16x16x32_bf16 v[10:13], v[176:179], v[222:225], v[10:13]
	v_mfma_f32_16x16x32_bf16 v[78:81], v[172:175], v[202:205], v[78:81]
	v_mfma_f32_16x16x32_bf16 v[74:77], v[180:183], v[202:205], v[74:77]
	v_mfma_f32_16x16x32_bf16 v[46:49], v[172:175], v[210:213], v[46:49]
	v_mfma_f32_16x16x32_bf16 v[42:45], v[180:183], v[210:213], v[42:45]
	v_mfma_f32_16x16x32_bf16 v[30:33], v[172:175], v[218:221], v[30:33]
	v_mfma_f32_16x16x32_bf16 v[26:29], v[180:183], v[218:221], v[26:29]
	v_mfma_f32_16x16x32_bf16 v[14:17], v[172:175], v[226:229], v[14:17]
	v_mfma_f32_16x16x32_bf16 v[10:13], v[180:183], v[226:229], v[10:13]
	s_barrier
	s_setprio 0
	s_add_u32 s40, s40, 0x100
	s_addc_u32 s49, s49, 0
	s_add_u32 s10, s10, 0x100
	s_addc_u32 s11, s11, 0
	s_cmp_ge_u32 vcc_lo, s19
	s_mov_b32 s38, vcc_lo
	s_cbranch_scc1 .Lpeel_done_0

.LBB0_1692:
	s_ashr_i32 s13, s12, 31
	s_lshl_b64 s[16:17], s[12:13], 18
	s_add_u32 s16, s45, s16
	s_addc_u32 s17, s44, s17
	s_and_b64 s[26:27], s[26:27], exec
	s_cselect_b32 s13, s17, s25
	s_cselect_b32 s15, s16, s24
	s_add_u32 s34, s24, 0x100
	s_addc_u32 s35, s25, 0
	s_add_u32 s22, s22, 0x80080
	s_addc_u32 s23, s23, 0
	s_mov_b32 s36, -2
	ds_read_b128 v[128:131], v169
	ds_read_b128 v[132:135], v169 offset:1024
	ds_read_b128 v[136:139], v169 offset:2048
	ds_read_b128 v[140:143], v169 offset:3072
	ds_read_b128 v[158:161], v170
	ds_read_b128 v[162:165], v170 offset:1024
	ds_read_b128 v[172:175], v170 offset:2048
	ds_read_b128 v[176:179], v170 offset:3072
	s_add_u32 s24, s22, 0xfff80080
	s_addc_u32 s25, s23, -1
	s_cmp_eq_u32 s36, 4
	s_cselect_b32 s27, s5, s25
	s_cselect_b32 s26, s4, s24
	s_cselect_b32 s25, s13, s35
	s_cselect_b32 s24, s15, s34
	s_add_i32 m0, s94, 0xc000
	ds_read_b128 v[180:183], v171
	ds_read_b128 v[184:187], v171 offset:1024
	ds_read_b128 v[188:191], v171 offset:2048
	ds_read_b128 v[192:195], v171 offset:3072
	ds_read_b128 v[196:199], v171 offset:4096
	ds_read_b128 v[200:203], v171 offset:5120
	ds_read_b128 v[204:207], v171 offset:6144
	ds_read_b128 v[208:211], v171 offset:7168
	global_load_lds_dwordx4 v152, s[22:23]
	s_add_i32 m0, s94, 0xe000
	s_nop 0
	global_load_lds_dwordx4 v154, s[22:23]
	s_waitcnt vmcnt(24)
	s_waitcnt lgkmcnt(0)
	s_setprio 1
	s_barrier
	v_mfma_f32_16x16x32_bf16 v[80:83], v[128:131], v[180:183], 0
	v_mfma_f32_16x16x32_bf16 v[92:95], v[136:139], v[180:183], 0
	v_mfma_f32_16x16x32_bf16 v[84:87], v[128:131], v[188:191], 0
	v_mfma_f32_16x16x32_bf16 v[96:99], v[136:139], v[188:191], 0
	v_mfma_f32_16x16x32_bf16 v[88:91], v[128:131], v[196:199], 0
	v_mfma_f32_16x16x32_bf16 v[100:103], v[136:139], v[196:199], 0
	v_mfma_f32_16x16x32_bf16 v[72:75], v[128:131], v[204:207], 0
	v_mfma_f32_16x16x32_bf16 v[76:79], v[136:139], v[204:207], 0
	v_mfma_f32_16x16x32_bf16 v[80:83], v[132:135], v[184:187], v[80:83]
	v_mfma_f32_16x16x32_bf16 v[92:95], v[140:143], v[184:187], v[92:95]
	v_mfma_f32_16x16x32_bf16 v[84:87], v[132:135], v[192:195], v[84:87]
	v_mfma_f32_16x16x32_bf16 v[96:99], v[140:143], v[192:195], v[96:99]
	v_mfma_f32_16x16x32_bf16 v[88:91], v[132:135], v[200:203], v[88:91]
	v_mfma_f32_16x16x32_bf16 v[100:103], v[140:143], v[200:203], v[100:103]
	v_mfma_f32_16x16x32_bf16 v[72:75], v[132:135], v[208:211], v[72:75]
	v_mfma_f32_16x16x32_bf16 v[76:79], v[140:143], v[208:211], v[76:79]
	s_setprio 0
	s_setprio 1
	v_mfma_f32_16x16x32_bf16 v[104:107], v[158:161], v[180:183], 0
	v_mfma_f32_16x16x32_bf16 v[116:119], v[172:175], v[180:183], 0
	v_mfma_f32_16x16x32_bf16 v[108:111], v[158:161], v[188:191], 0
	v_mfma_f32_16x16x32_bf16 v[120:123], v[172:175], v[188:191], 0
	v_mfma_f32_16x16x32_bf16 v[112:115], v[158:161], v[196:199], 0
	v_mfma_f32_16x16x32_bf16 v[124:127], v[172:175], v[196:199], 0
	v_mfma_f32_16x16x32_bf16 v[68:71], v[158:161], v[204:207], 0
	v_mfma_f32_16x16x32_bf16 v[64:67], v[172:175], v[204:207], 0
	v_mfma_f32_16x16x32_bf16 v[104:107], v[162:165], v[184:187], v[104:107]
	v_mfma_f32_16x16x32_bf16 v[116:119], v[176:179], v[184:187], v[116:119]
	v_mfma_f32_16x16x32_bf16 v[108:111], v[162:165], v[192:195], v[108:111]
	v_mfma_f32_16x16x32_bf16 v[120:123], v[176:179], v[192:195], v[120:123]
	v_mfma_f32_16x16x32_bf16 v[112:115], v[162:165], v[200:203], v[112:115]
	v_mfma_f32_16x16x32_bf16 v[124:127], v[176:179], v[200:203], v[124:127]
	v_mfma_f32_16x16x32_bf16 v[68:71], v[162:165], v[208:211], v[68:71]
	v_mfma_f32_16x16x32_bf16 v[64:67], v[176:179], v[208:211], v[64:67]
	s_barrier
	s_setprio 0
	s_add_i32 s37, s31, s97
	s_add_u32 s98, s24, 0x80
	s_addc_u32 s99, s25, 0
	s_mov_b32 m0, s37
	ds_read_b128 v[180:183], v171 offset:16384
	ds_read_b128 v[184:187], v171 offset:17408
	ds_read_b128 v[188:191], v171 offset:18432
	ds_read_b128 v[192:195], v171 offset:19456
	ds_read_b128 v[196:199], v171 offset:20480
	ds_read_b128 v[200:203], v171 offset:21504
	ds_read_b128 v[204:207], v171 offset:22528
	ds_read_b128 v[208:211], v171 offset:23552
	global_load_lds_dwordx4 v148, s[24:25]
	s_add_i32 m0, s37, 0x2000
	s_add_u32 s38, s24, 0x20000
	s_addc_u32 s39, s25, 0
	s_add_i32 s37, s33, s97
	global_load_lds_dwordx4 v144, s[24:25]
	s_mov_b32 m0, s37
	s_add_u32 s100, s26, 0x80
	s_addc_u32 s101, s27, 0
	global_load_lds_dwordx4 v148, s[38:39]
	s_add_i32 m0, s37, 0x2000
	s_nop 0
	global_load_lds_dwordx4 v144, s[38:39]
	s_mov_b32 m0, s94
	s_nop 0
	global_load_lds_dwordx4 v150, s[26:27]
	s_mov_b32 m0, s3
	s_nop 0
	global_load_lds_dwordx4 v146, s[26:27]
	s_waitcnt vmcnt(8)
	s_waitcnt lgkmcnt(0)
	s_setprio 1
	s_barrier
	v_mfma_f32_16x16x32_bf16 v[48:51], v[128:131], v[180:183], 0
	v_mfma_f32_16x16x32_bf16 v[52:55], v[136:139], v[180:183], 0
	v_mfma_f32_16x16x32_bf16 v[32:35], v[128:131], v[188:191], 0
	v_mfma_f32_16x16x32_bf16 v[36:39], v[136:139], v[188:191], 0
	v_mfma_f32_16x16x32_bf16 v[16:19], v[128:131], v[196:199], 0
	v_mfma_f32_16x16x32_bf16 v[20:23], v[136:139], v[196:199], 0
	v_mfma_f32_16x16x32_bf16 v[0:3], v[128:131], v[204:207], 0
	v_mfma_f32_16x16x32_bf16 v[4:7], v[136:139], v[204:207], 0
	v_mfma_f32_16x16x32_bf16 v[48:51], v[132:135], v[184:187], v[48:51]
	v_mfma_f32_16x16x32_bf16 v[52:55], v[140:143], v[184:187], v[52:55]
	v_mfma_f32_16x16x32_bf16 v[32:35], v[132:135], v[192:195], v[32:35]
	v_mfma_f32_16x16x32_bf16 v[36:39], v[140:143], v[192:195], v[36:39]
	v_mfma_f32_16x16x32_bf16 v[16:19], v[132:135], v[200:203], v[16:19]
	v_mfma_f32_16x16x32_bf16 v[20:23], v[140:143], v[200:203], v[20:23]
	v_mfma_f32_16x16x32_bf16 v[0:3], v[132:135], v[208:211], v[0:3]
	v_mfma_f32_16x16x32_bf16 v[4:7], v[140:143], v[208:211], v[4:7]
	s_setprio 0
	s_setprio 1
	v_mfma_f32_16x16x32_bf16 v[56:59], v[158:161], v[180:183], 0
	v_mfma_f32_16x16x32_bf16 v[60:63], v[172:175], v[180:183], 0
	v_mfma_f32_16x16x32_bf16 v[40:43], v[158:161], v[188:191], 0
	v_mfma_f32_16x16x32_bf16 v[44:47], v[172:175], v[188:191], 0
	v_mfma_f32_16x16x32_bf16 v[24:27], v[158:161], v[196:199], 0
	v_mfma_f32_16x16x32_bf16 v[28:31], v[172:175], v[196:199], 0
	v_mfma_f32_16x16x32_bf16 v[8:11], v[158:161], v[204:207], 0
	v_mfma_f32_16x16x32_bf16 v[12:15], v[172:175], v[204:207], 0
	v_mfma_f32_16x16x32_bf16 v[56:59], v[162:165], v[184:187], v[56:59]
	v_mfma_f32_16x16x32_bf16 v[60:63], v[176:179], v[184:187], v[60:63]
	v_mfma_f32_16x16x32_bf16 v[40:43], v[162:165], v[192:195], v[40:43]
	v_mfma_f32_16x16x32_bf16 v[44:47], v[176:179], v[192:195], v[44:47]
	v_mfma_f32_16x16x32_bf16 v[24:27], v[162:165], v[200:203], v[24:27]
	v_mfma_f32_16x16x32_bf16 v[28:31], v[176:179], v[200:203], v[28:31]
	v_mfma_f32_16x16x32_bf16 v[8:11], v[162:165], v[208:211], v[8:11]
	v_mfma_f32_16x16x32_bf16 v[12:15], v[176:179], v[208:211], v[12:15]
	s_barrier
	s_setprio 0
	s_add_i32 s37, 0, 0x18000
	s_add_i32 s38, 0, 0x1c000
	v_add_u32_e32 v140, s37, v167
	v_add_u32_e32 v176, s38, v167
	ds_read_b128 v[128:131], v140
	ds_read_b128 v[132:135], v140 offset:1024
	ds_read_b128 v[136:139], v140 offset:2048
	ds_read_b128 v[140:143], v140 offset:3072
	ds_read_b128 v[158:161], v176
	ds_read_b128 v[162:165], v176 offset:1024
	ds_read_b128 v[172:175], v176 offset:2048
	ds_read_b128 v[176:179], v176 offset:3072
	s_add_u32 s26, s26, 0x80000
	s_addc_u32 s27, s27, 0
	s_mov_b32 m0, s7
	ds_read_b128 v[180:183], v171 offset:32768
	ds_read_b128 v[184:187], v171 offset:33792
	ds_read_b128 v[188:191], v171 offset:34816
	ds_read_b128 v[192:195], v171 offset:35840
	ds_read_b128 v[196:199], v171 offset:36864
	ds_read_b128 v[200:203], v171 offset:37888
	ds_read_b128 v[204:207], v171 offset:38912
	ds_read_b128 v[208:211], v171 offset:39936
	global_load_lds_dwordx4 v150, s[26:27]
	s_mov_b32 m0, s19
	s_nop 0
	global_load_lds_dwordx4 v146, s[26:27]
	s_waitcnt vmcnt(8)
	s_waitcnt lgkmcnt(0)
	s_setprio 1
	s_barrier
	v_mfma_f32_16x16x32_bf16 v[80:83], v[128:131], v[180:183], v[80:83]
	v_mfma_f32_16x16x32_bf16 v[92:95], v[136:139], v[180:183], v[92:95]
	v_mfma_f32_16x16x32_bf16 v[84:87], v[128:131], v[188:191], v[84:87]
	v_mfma_f32_16x16x32_bf16 v[96:99], v[136:139], v[188:191], v[96:99]
	v_mfma_f32_16x16x32_bf16 v[88:91], v[128:131], v[196:199], v[88:91]
	v_mfma_f32_16x16x32_bf16 v[100:103], v[136:139], v[196:199], v[100:103]
	v_mfma_f32_16x16x32_bf16 v[72:75], v[128:131], v[204:207], v[72:75]
	v_mfma_f32_16x16x32_bf16 v[76:79], v[136:139], v[204:207], v[76:79]
	v_mfma_f32_16x16x32_bf16 v[80:83], v[132:135], v[184:187], v[80:83]
	v_mfma_f32_16x16x32_bf16 v[92:95], v[140:143], v[184:187], v[92:95]
	v_mfma_f32_16x16x32_bf16 v[84:87], v[132:135], v[192:195], v[84:87]
	v_mfma_f32_16x16x32_bf16 v[96:99], v[140:143], v[192:195], v[96:99]
	v_mfma_f32_16x16x32_bf16 v[88:91], v[132:135], v[200:203], v[88:91]
	v_mfma_f32_16x16x32_bf16 v[100:103], v[140:143], v[200:203], v[100:103]
	v_mfma_f32_16x16x32_bf16 v[72:75], v[132:135], v[208:211], v[72:75]
	v_mfma_f32_16x16x32_bf16 v[76:79], v[140:143], v[208:211], v[76:79]
	s_setprio 0
	s_setprio 1
	v_mfma_f32_16x16x32_bf16 v[104:107], v[158:161], v[180:183], v[104:107]
	v_mfma_f32_16x16x32_bf16 v[116:119], v[172:175], v[180:183], v[116:119]
	v_mfma_f32_16x16x32_bf16 v[108:111], v[158:161], v[188:191], v[108:111]
	v_mfma_f32_16x16x32_bf16 v[120:123], v[172:175], v[188:191], v[120:123]
	v_mfma_f32_16x16x32_bf16 v[112:115], v[158:161], v[196:199], v[112:115]
	v_mfma_f32_16x16x32_bf16 v[124:127], v[172:175], v[196:199], v[124:127]
	v_mfma_f32_16x16x32_bf16 v[68:71], v[158:161], v[204:207], v[68:71]
	v_mfma_f32_16x16x32_bf16 v[64:67], v[172:175], v[204:207], v[64:67]
	v_mfma_f32_16x16x32_bf16 v[104:107], v[162:165], v[184:187], v[104:107]
	v_mfma_f32_16x16x32_bf16 v[116:119], v[176:179], v[184:187], v[116:119]
	v_mfma_f32_16x16x32_bf16 v[108:111], v[162:165], v[192:195], v[108:111]
	v_mfma_f32_16x16x32_bf16 v[120:123], v[176:179], v[192:195], v[120:123]
	v_mfma_f32_16x16x32_bf16 v[112:115], v[162:165], v[200:203], v[112:115]
	v_mfma_f32_16x16x32_bf16 v[124:127], v[176:179], v[200:203], v[124:127]
	v_mfma_f32_16x16x32_bf16 v[68:71], v[162:165], v[208:211], v[68:71]
	v_mfma_f32_16x16x32_bf16 v[64:67], v[176:179], v[208:211], v[64:67]
	s_barrier
	s_setprio 0
	s_add_i32 s26, s37, s97
	s_mov_b32 m0, s26
	ds_read_b128 v[180:183], v171 offset:49152
	ds_read_b128 v[184:187], v171 offset:50176
	ds_read_b128 v[188:191], v171 offset:51200
	ds_read_b128 v[192:195], v171 offset:52224
	ds_read_b128 v[196:199], v171 offset:53248
	ds_read_b128 v[200:203], v171 offset:54272
	ds_read_b128 v[204:207], v171 offset:55296
	ds_read_b128 v[208:211], v171 offset:56320
	global_load_lds_dwordx4 v148, s[98:99]
	s_add_i32 m0, s26, 0x2000
	s_add_u32 s24, s24, 0x20080
	s_addc_u32 s25, s25, 0
	s_add_i32 s26, s38, s97
	global_load_lds_dwordx4 v144, s[98:99]
	s_mov_b32 m0, s26
	s_nop 0
	global_load_lds_dwordx4 v148, s[24:25]
	s_add_i32 m0, s26, 0x2000
	s_nop 0
	global_load_lds_dwordx4 v144, s[24:25]
	s_mov_b32 m0, s28
	s_nop 0
	global_load_lds_dwordx4 v150, s[100:101]
	s_mov_b32 m0, s29
	s_nop 0
	global_load_lds_dwordx4 v146, s[100:101]
	s_waitcnt vmcnt(8)
	s_waitcnt lgkmcnt(0)
	s_setprio 1
	s_barrier
	v_mfma_f32_16x16x32_bf16 v[48:51], v[128:131], v[180:183], v[48:51]
	v_mfma_f32_16x16x32_bf16 v[52:55], v[136:139], v[180:183], v[52:55]
	v_mfma_f32_16x16x32_bf16 v[32:35], v[128:131], v[188:191], v[32:35]
	v_mfma_f32_16x16x32_bf16 v[36:39], v[136:139], v[188:191], v[36:39]
	v_mfma_f32_16x16x32_bf16 v[16:19], v[128:131], v[196:199], v[16:19]
	v_mfma_f32_16x16x32_bf16 v[20:23], v[136:139], v[196:199], v[20:23]
	v_mfma_f32_16x16x32_bf16 v[0:3], v[128:131], v[204:207], v[0:3]
	v_mfma_f32_16x16x32_bf16 v[4:7], v[136:139], v[204:207], v[4:7]
	v_mfma_f32_16x16x32_bf16 v[48:51], v[132:135], v[184:187], v[48:51]
	v_mfma_f32_16x16x32_bf16 v[52:55], v[140:143], v[184:187], v[52:55]
	v_mfma_f32_16x16x32_bf16 v[32:35], v[132:135], v[192:195], v[32:35]
	v_mfma_f32_16x16x32_bf16 v[36:39], v[140:143], v[192:195], v[36:39]
	v_mfma_f32_16x16x32_bf16 v[16:19], v[132:135], v[200:203], v[16:19]
	v_mfma_f32_16x16x32_bf16 v[20:23], v[140:143], v[200:203], v[20:23]
	v_mfma_f32_16x16x32_bf16 v[0:3], v[132:135], v[208:211], v[0:3]
	v_mfma_f32_16x16x32_bf16 v[4:7], v[140:143], v[208:211], v[4:7]
	s_setprio 0
	s_setprio 1
	v_mfma_f32_16x16x32_bf16 v[56:59], v[158:161], v[180:183], v[56:59]
	v_mfma_f32_16x16x32_bf16 v[60:63], v[172:175], v[180:183], v[60:63]
	v_mfma_f32_16x16x32_bf16 v[40:43], v[158:161], v[188:191], v[40:43]
	v_mfma_f32_16x16x32_bf16 v[44:47], v[172:175], v[188:191], v[44:47]
	v_mfma_f32_16x16x32_bf16 v[24:27], v[158:161], v[196:199], v[24:27]
	v_mfma_f32_16x16x32_bf16 v[28:31], v[172:175], v[196:199], v[28:31]
	v_mfma_f32_16x16x32_bf16 v[8:11], v[158:161], v[204:207], v[8:11]
	v_mfma_f32_16x16x32_bf16 v[12:15], v[172:175], v[204:207], v[12:15]
	v_mfma_f32_16x16x32_bf16 v[56:59], v[162:165], v[184:187], v[56:59]
	v_mfma_f32_16x16x32_bf16 v[60:63], v[176:179], v[184:187], v[60:63]
	v_mfma_f32_16x16x32_bf16 v[40:43], v[162:165], v[192:195], v[40:43]
	v_mfma_f32_16x16x32_bf16 v[44:47], v[176:179], v[192:195], v[44:47]
	v_mfma_f32_16x16x32_bf16 v[24:27], v[162:165], v[200:203], v[24:27]
	v_mfma_f32_16x16x32_bf16 v[28:31], v[176:179], v[200:203], v[28:31]
	v_mfma_f32_16x16x32_bf16 v[8:11], v[162:165], v[208:211], v[8:11]
	v_mfma_f32_16x16x32_bf16 v[12:15], v[176:179], v[208:211], v[12:15]
	s_barrier
	s_setprio 0
	s_add_i32 s36, s36, 2
	s_add_u32 s34, s34, 0x100
	s_addc_u32 s35, s35, 0
	s_add_u32 s22, s22, 0x100
	s_addc_u32 s23, s23, 0
	s_cmp_gt_u32 s36, 5
	s_cbranch_scc1 .Lpeel_done_1

.LBB0_2019:
	s_cmp_lt_u32 s5, 0x3fffffff
	s_cselect_b64 s[40:41], -1, 0
	s_ashr_i32 s23, s22, 31
	s_and_b64 s[40:41], s[36:37], s[40:41]
	s_lshl_b64 s[36:37], s[22:23], 21
	s_add_u32 s5, s86, s36
	s_addc_u32 s21, s87, s37
	s_add_u32 s36, s5, s38
	s_addc_u32 s37, s21, s39
	s_and_b64 s[48:49], s[40:41], exec
	s_cselect_b32 s5, s37, s47
	s_cselect_b32 s23, s36, s46
	s_ashr_i32 s21, s20, 31
	s_lshl_b64 s[48:49], s[20:21], 21
	v_readlane_b32 s68, v254, 13
	v_readlane_b32 s69, v254, 14
	s_add_u32 s21, s68, s48
	s_addc_u32 s43, s69, s49
	s_add_u32 s38, s21, s38
	s_addc_u32 s39, s43, s39
	s_and_b64 s[48:49], s[40:41], exec
	s_cselect_b32 s21, s39, s45
	s_cselect_b32 s43, s38, s44
	s_add_i32 s68, s67, -2
	s_add_u32 s69, s44, 0x100
	s_addc_u32 s70, s45, 0
	s_add_u32 s44, s46, 0x100080
	s_addc_u32 s45, s47, 0
	s_mov_b32 s46, 0
	s_waitcnt vmcnt(0)
	ds_read_b128 v[128:131], v244
	ds_read_b128 v[132:135], v244 offset:1024
	ds_read_b128 v[136:139], v244 offset:2048
	ds_read_b128 v[140:143], v244 offset:3072
	ds_read_b128 v[144:147], v245
	ds_read_b128 v[148:151], v245 offset:1024
	ds_read_b128 v[152:155], v245 offset:2048
	ds_read_b128 v[156:159], v245 offset:3072
	s_add_i32 s71, s46, 2
	s_add_u32 s47, s44, 0xfff00080
	s_addc_u32 s48, s45, -1
	s_cmp_eq_u32 s68, s46
	s_cselect_b32 s46, s43, s69
	s_cselect_b32 s49, s5, s48
	s_cselect_b32 s48, s23, s47
	s_cselect_b32 s47, s21, s70
	s_add_i32 m0, s94, 0xc000
	ds_read_b128 v[160:163], v246
	ds_read_b128 v[164:167], v246 offset:1024
	ds_read_b128 v[168:171], v246 offset:2048
	ds_read_b128 v[172:175], v246 offset:3072
	ds_read_b128 v[176:179], v246 offset:4096
	ds_read_b128 v[180:183], v246 offset:5120
	ds_read_b128 v[184:187], v246 offset:6144
	ds_read_b128 v[188:191], v246 offset:7168
	global_load_lds_dwordx4 v218, s[44:45]
	s_add_i32 m0, s94, 0xe000
	s_nop 0
	global_load_lds_dwordx4 v220, s[44:45]
	s_waitcnt vmcnt(24)
	s_waitcnt lgkmcnt(0)
	s_setprio 1
	s_barrier
	v_mfma_f32_16x16x32_bf16 v[112:115], v[128:131], v[160:163], 0
	v_mfma_f32_16x16x32_bf16 v[116:119], v[136:139], v[160:163], 0
	v_mfma_f32_16x16x32_bf16 v[100:103], v[128:131], v[168:171], 0
	v_mfma_f32_16x16x32_bf16 v[96:99], v[136:139], v[168:171], 0
	v_mfma_f32_16x16x32_bf16 v[84:87], v[128:131], v[176:179], 0
	v_mfma_f32_16x16x32_bf16 v[80:83], v[136:139], v[176:179], 0
	v_mfma_f32_16x16x32_bf16 v[52:55], v[128:131], v[184:187], 0
	v_mfma_f32_16x16x32_bf16 v[48:51], v[136:139], v[184:187], 0
	v_mfma_f32_16x16x32_bf16 v[112:115], v[132:135], v[164:167], v[112:115]
	v_mfma_f32_16x16x32_bf16 v[116:119], v[140:143], v[164:167], v[116:119]
	v_mfma_f32_16x16x32_bf16 v[100:103], v[132:135], v[172:175], v[100:103]
	v_mfma_f32_16x16x32_bf16 v[96:99], v[140:143], v[172:175], v[96:99]
	v_mfma_f32_16x16x32_bf16 v[84:87], v[132:135], v[180:183], v[84:87]
	v_mfma_f32_16x16x32_bf16 v[80:83], v[140:143], v[180:183], v[80:83]
	v_mfma_f32_16x16x32_bf16 v[52:55], v[132:135], v[188:191], v[52:55]
	v_mfma_f32_16x16x32_bf16 v[48:51], v[140:143], v[188:191], v[48:51]
	s_setprio 0
	s_setprio 1
	v_mfma_f32_16x16x32_bf16 v[124:127], v[144:147], v[160:163], 0
	v_mfma_f32_16x16x32_bf16 v[120:123], v[152:155], v[160:163], 0
	v_mfma_f32_16x16x32_bf16 v[108:111], v[144:147], v[168:171], 0
	v_mfma_f32_16x16x32_bf16 v[104:107], v[152:155], v[168:171], 0
	v_mfma_f32_16x16x32_bf16 v[92:95], v[144:147], v[176:179], 0
	v_mfma_f32_16x16x32_bf16 v[88:91], v[152:155], v[176:179], 0
	v_mfma_f32_16x16x32_bf16 v[68:71], v[144:147], v[184:187], 0
	v_mfma_f32_16x16x32_bf16 v[64:67], v[152:155], v[184:187], 0
	v_mfma_f32_16x16x32_bf16 v[124:127], v[148:151], v[164:167], v[124:127]
	v_mfma_f32_16x16x32_bf16 v[120:123], v[156:159], v[164:167], v[120:123]
	v_mfma_f32_16x16x32_bf16 v[108:111], v[148:151], v[172:175], v[108:111]
	v_mfma_f32_16x16x32_bf16 v[104:107], v[156:159], v[172:175], v[104:107]
	v_mfma_f32_16x16x32_bf16 v[92:95], v[148:151], v[180:183], v[92:95]
	v_mfma_f32_16x16x32_bf16 v[88:91], v[156:159], v[180:183], v[88:91]
	v_mfma_f32_16x16x32_bf16 v[68:71], v[148:151], v[188:191], v[68:71]
	v_mfma_f32_16x16x32_bf16 v[64:67], v[156:159], v[188:191], v[64:67]
	s_barrier
	s_setprio 0
	s_add_i32 s76, s60, s97
	s_add_u32 s98, s46, 0x80
	s_addc_u32 s99, s47, 0
	s_mov_b32 m0, s76
	ds_read_b128 v[160:163], v246 offset:16384
	ds_read_b128 v[164:167], v246 offset:17408
	ds_read_b128 v[168:171], v246 offset:18432
	ds_read_b128 v[172:175], v246 offset:19456
	ds_read_b128 v[176:179], v246 offset:20480
	ds_read_b128 v[180:183], v246 offset:21504
	ds_read_b128 v[184:187], v246 offset:22528
	ds_read_b128 v[188:191], v246 offset:23552
	global_load_lds_dwordx4 v210, s[46:47]
	s_add_i32 m0, s76, 0x2000
	s_add_u32 s76, s46, 0x100000
	s_addc_u32 s77, s47, 0
	s_add_i32 s78, s61, s97
	global_load_lds_dwordx4 v214, s[46:47]
	s_mov_b32 m0, s78
	s_add_u32 s100, s48, 0x80
	s_addc_u32 s101, s49, 0
	global_load_lds_dwordx4 v210, s[76:77]
	s_add_i32 m0, s78, 0x2000
	s_nop 0
	global_load_lds_dwordx4 v214, s[76:77]
	s_mov_b32 m0, s94
	s_nop 0
	global_load_lds_dwordx4 v208, s[48:49]
	s_mov_b32 m0, s2
	s_nop 0
	global_load_lds_dwordx4 v212, s[48:49]
	s_waitcnt vmcnt(8)
	s_waitcnt lgkmcnt(0)
	s_setprio 1
	s_barrier
	v_mfma_f32_16x16x32_bf16 v[60:63], v[128:131], v[160:163], 0
	v_mfma_f32_16x16x32_bf16 v[56:59], v[136:139], v[160:163], 0
	v_mfma_f32_16x16x32_bf16 v[36:39], v[128:131], v[168:171], 0
	v_mfma_f32_16x16x32_bf16 v[32:35], v[136:139], v[168:171], 0
	v_mfma_f32_16x16x32_bf16 v[20:23], v[128:131], v[176:179], 0
	v_mfma_f32_16x16x32_bf16 v[16:19], v[136:139], v[176:179], 0
	v_mfma_f32_16x16x32_bf16 v[4:7], v[128:131], v[184:187], 0
	v_mfma_f32_16x16x32_bf16 v[0:3], v[136:139], v[184:187], 0
	v_mfma_f32_16x16x32_bf16 v[60:63], v[132:135], v[164:167], v[60:63]
	v_mfma_f32_16x16x32_bf16 v[56:59], v[140:143], v[164:167], v[56:59]
	v_mfma_f32_16x16x32_bf16 v[36:39], v[132:135], v[172:175], v[36:39]
	v_mfma_f32_16x16x32_bf16 v[32:35], v[140:143], v[172:175], v[32:35]
	v_mfma_f32_16x16x32_bf16 v[20:23], v[132:135], v[180:183], v[20:23]
	v_mfma_f32_16x16x32_bf16 v[16:19], v[140:143], v[180:183], v[16:19]
	v_mfma_f32_16x16x32_bf16 v[4:7], v[132:135], v[188:191], v[4:7]
	v_mfma_f32_16x16x32_bf16 v[0:3], v[140:143], v[188:191], v[0:3]
	s_setprio 0
	s_setprio 1
	v_mfma_f32_16x16x32_bf16 v[76:79], v[144:147], v[160:163], 0
	v_mfma_f32_16x16x32_bf16 v[72:75], v[152:155], v[160:163], 0
	v_mfma_f32_16x16x32_bf16 v[44:47], v[144:147], v[168:171], 0
	v_mfma_f32_16x16x32_bf16 v[40:43], v[152:155], v[168:171], 0
	v_mfma_f32_16x16x32_bf16 v[28:31], v[144:147], v[176:179], 0
	v_mfma_f32_16x16x32_bf16 v[24:27], v[152:155], v[176:179], 0
	v_mfma_f32_16x16x32_bf16 v[12:15], v[144:147], v[184:187], 0
	v_mfma_f32_16x16x32_bf16 v[8:11], v[152:155], v[184:187], 0
	v_mfma_f32_16x16x32_bf16 v[76:79], v[148:151], v[164:167], v[76:79]
	v_mfma_f32_16x16x32_bf16 v[72:75], v[156:159], v[164:167], v[72:75]
	v_mfma_f32_16x16x32_bf16 v[44:47], v[148:151], v[172:175], v[44:47]
	v_mfma_f32_16x16x32_bf16 v[40:43], v[156:159], v[172:175], v[40:43]
	v_mfma_f32_16x16x32_bf16 v[28:31], v[148:151], v[180:183], v[28:31]
	v_mfma_f32_16x16x32_bf16 v[24:27], v[156:159], v[180:183], v[24:27]
	v_mfma_f32_16x16x32_bf16 v[12:15], v[148:151], v[188:191], v[12:15]
	v_mfma_f32_16x16x32_bf16 v[8:11], v[156:159], v[188:191], v[8:11]
	s_barrier
	s_setprio 0
	s_add_i32 s76, 0, 0x18000
	s_add_i32 s77, 0, 0x1c000
	v_add_u32_e32 v140, s76, v243
	v_add_u32_e32 v156, s77, v243
	ds_read_b128 v[128:131], v140
	ds_read_b128 v[132:135], v140 offset:1024
	ds_read_b128 v[136:139], v140 offset:2048
	ds_read_b128 v[140:143], v140 offset:3072
	ds_read_b128 v[144:147], v156
	ds_read_b128 v[148:151], v156 offset:1024
	ds_read_b128 v[152:155], v156 offset:2048
	ds_read_b128 v[156:159], v156 offset:3072
	s_add_u32 s48, s48, 0x100000
	s_addc_u32 s49, s49, 0
	s_mov_b32 m0, s3
	ds_read_b128 v[160:163], v246 offset:32768
	ds_read_b128 v[164:167], v246 offset:33792
	ds_read_b128 v[168:171], v246 offset:34816
	ds_read_b128 v[172:175], v246 offset:35840
	ds_read_b128 v[176:179], v246 offset:36864
	ds_read_b128 v[180:183], v246 offset:37888
	ds_read_b128 v[184:187], v246 offset:38912
	ds_read_b128 v[188:191], v246 offset:39936
	global_load_lds_dwordx4 v208, s[48:49]
	s_mov_b32 m0, s33
	s_nop 0
	global_load_lds_dwordx4 v212, s[48:49]
	s_waitcnt vmcnt(8)
	s_waitcnt lgkmcnt(0)
	s_setprio 1
	s_barrier
	v_mfma_f32_16x16x32_bf16 v[112:115], v[128:131], v[160:163], v[112:115]
	v_mfma_f32_16x16x32_bf16 v[116:119], v[136:139], v[160:163], v[116:119]
	v_mfma_f32_16x16x32_bf16 v[100:103], v[128:131], v[168:171], v[100:103]
	v_mfma_f32_16x16x32_bf16 v[96:99], v[136:139], v[168:171], v[96:99]
	v_mfma_f32_16x16x32_bf16 v[84:87], v[128:131], v[176:179], v[84:87]
	v_mfma_f32_16x16x32_bf16 v[80:83], v[136:139], v[176:179], v[80:83]
	v_mfma_f32_16x16x32_bf16 v[52:55], v[128:131], v[184:187], v[52:55]
	v_mfma_f32_16x16x32_bf16 v[48:51], v[136:139], v[184:187], v[48:51]
	v_mfma_f32_16x16x32_bf16 v[112:115], v[132:135], v[164:167], v[112:115]
	v_mfma_f32_16x16x32_bf16 v[116:119], v[140:143], v[164:167], v[116:119]
	v_mfma_f32_16x16x32_bf16 v[100:103], v[132:135], v[172:175], v[100:103]
	v_mfma_f32_16x16x32_bf16 v[96:99], v[140:143], v[172:175], v[96:99]
	v_mfma_f32_16x16x32_bf16 v[84:87], v[132:135], v[180:183], v[84:87]
	v_mfma_f32_16x16x32_bf16 v[80:83], v[140:143], v[180:183], v[80:83]
	v_mfma_f32_16x16x32_bf16 v[52:55], v[132:135], v[188:191], v[52:55]
	v_mfma_f32_16x16x32_bf16 v[48:51], v[140:143], v[188:191], v[48:51]
	s_setprio 0
	s_setprio 1
	v_mfma_f32_16x16x32_bf16 v[124:127], v[144:147], v[160:163], v[124:127]
	v_mfma_f32_16x16x32_bf16 v[120:123], v[152:155], v[160:163], v[120:123]
	v_mfma_f32_16x16x32_bf16 v[108:111], v[144:147], v[168:171], v[108:111]
	v_mfma_f32_16x16x32_bf16 v[104:107], v[152:155], v[168:171], v[104:107]
	v_mfma_f32_16x16x32_bf16 v[92:95], v[144:147], v[176:179], v[92:95]
	v_mfma_f32_16x16x32_bf16 v[88:91], v[152:155], v[176:179], v[88:91]
	v_mfma_f32_16x16x32_bf16 v[68:71], v[144:147], v[184:187], v[68:71]
	v_mfma_f32_16x16x32_bf16 v[64:67], v[152:155], v[184:187], v[64:67]
	v_mfma_f32_16x16x32_bf16 v[124:127], v[148:151], v[164:167], v[124:127]
	v_mfma_f32_16x16x32_bf16 v[120:123], v[156:159], v[164:167], v[120:123]
	v_mfma_f32_16x16x32_bf16 v[108:111], v[148:151], v[172:175], v[108:111]
	v_mfma_f32_16x16x32_bf16 v[104:107], v[156:159], v[172:175], v[104:107]
	v_mfma_f32_16x16x32_bf16 v[92:95], v[148:151], v[180:183], v[92:95]
	v_mfma_f32_16x16x32_bf16 v[88:91], v[156:159], v[180:183], v[88:91]
	v_mfma_f32_16x16x32_bf16 v[68:71], v[148:151], v[188:191], v[68:71]
	v_mfma_f32_16x16x32_bf16 v[64:67], v[156:159], v[188:191], v[64:67]
	s_barrier
	s_setprio 0
	s_add_i32 s48, s76, s97
	s_mov_b32 m0, s48
	ds_read_b128 v[160:163], v246 offset:49152
	ds_read_b128 v[164:167], v246 offset:50176
	ds_read_b128 v[168:171], v246 offset:51200
	ds_read_b128 v[172:175], v246 offset:52224
	ds_read_b128 v[176:179], v246 offset:53248
	ds_read_b128 v[180:183], v246 offset:54272
	ds_read_b128 v[184:187], v246 offset:55296
	ds_read_b128 v[188:191], v246 offset:56320
	global_load_lds_dwordx4 v210, s[98:99]
	s_add_i32 m0, s48, 0x2000
	s_add_u32 s46, s46, 0x100080
	s_addc_u32 s47, s47, 0
	s_add_i32 s48, s77, s97
	global_load_lds_dwordx4 v214, s[98:99]
	s_mov_b32 m0, s48
	s_nop 0
	global_load_lds_dwordx4 v210, s[46:47]
	s_add_i32 m0, s48, 0x2000
	s_nop 0
	global_load_lds_dwordx4 v214, s[46:47]
	s_mov_b32 m0, s54
	s_nop 0
	global_load_lds_dwordx4 v208, s[100:101]
	s_mov_b32 m0, s55
	s_nop 0
	global_load_lds_dwordx4 v212, s[100:101]
	s_waitcnt vmcnt(8)
	s_waitcnt lgkmcnt(0)
	s_setprio 1
	s_barrier
	v_mfma_f32_16x16x32_bf16 v[60:63], v[128:131], v[160:163], v[60:63]
	v_mfma_f32_16x16x32_bf16 v[56:59], v[136:139], v[160:163], v[56:59]
	v_mfma_f32_16x16x32_bf16 v[36:39], v[128:131], v[168:171], v[36:39]
	v_mfma_f32_16x16x32_bf16 v[32:35], v[136:139], v[168:171], v[32:35]
	v_mfma_f32_16x16x32_bf16 v[20:23], v[128:131], v[176:179], v[20:23]
	v_mfma_f32_16x16x32_bf16 v[16:19], v[136:139], v[176:179], v[16:19]
	v_mfma_f32_16x16x32_bf16 v[4:7], v[128:131], v[184:187], v[4:7]
	v_mfma_f32_16x16x32_bf16 v[0:3], v[136:139], v[184:187], v[0:3]
	v_mfma_f32_16x16x32_bf16 v[60:63], v[132:135], v[164:167], v[60:63]
	v_mfma_f32_16x16x32_bf16 v[56:59], v[140:143], v[164:167], v[56:59]
	v_mfma_f32_16x16x32_bf16 v[36:39], v[132:135], v[172:175], v[36:39]
	v_mfma_f32_16x16x32_bf16 v[32:35], v[140:143], v[172:175], v[32:35]
	v_mfma_f32_16x16x32_bf16 v[20:23], v[132:135], v[180:183], v[20:23]
	v_mfma_f32_16x16x32_bf16 v[16:19], v[140:143], v[180:183], v[16:19]
	v_mfma_f32_16x16x32_bf16 v[4:7], v[132:135], v[188:191], v[4:7]
	v_mfma_f32_16x16x32_bf16 v[0:3], v[140:143], v[188:191], v[0:3]
	s_setprio 0
	s_setprio 1
	v_mfma_f32_16x16x32_bf16 v[76:79], v[144:147], v[160:163], v[76:79]
	v_mfma_f32_16x16x32_bf16 v[72:75], v[152:155], v[160:163], v[72:75]
	v_mfma_f32_16x16x32_bf16 v[44:47], v[144:147], v[168:171], v[44:47]
	v_mfma_f32_16x16x32_bf16 v[40:43], v[152:155], v[168:171], v[40:43]
	v_mfma_f32_16x16x32_bf16 v[28:31], v[144:147], v[176:179], v[28:31]
	v_mfma_f32_16x16x32_bf16 v[24:27], v[152:155], v[176:179], v[24:27]
	v_mfma_f32_16x16x32_bf16 v[12:15], v[144:147], v[184:187], v[12:15]
	v_mfma_f32_16x16x32_bf16 v[8:11], v[152:155], v[184:187], v[8:11]
	v_mfma_f32_16x16x32_bf16 v[76:79], v[148:151], v[164:167], v[76:79]
	v_mfma_f32_16x16x32_bf16 v[72:75], v[156:159], v[164:167], v[72:75]
	v_mfma_f32_16x16x32_bf16 v[44:47], v[148:151], v[172:175], v[44:47]
	v_mfma_f32_16x16x32_bf16 v[40:43], v[156:159], v[172:175], v[40:43]
	v_mfma_f32_16x16x32_bf16 v[28:31], v[148:151], v[180:183], v[28:31]
	v_mfma_f32_16x16x32_bf16 v[24:27], v[156:159], v[180:183], v[24:27]
	v_mfma_f32_16x16x32_bf16 v[12:15], v[148:151], v[188:191], v[12:15]
	v_mfma_f32_16x16x32_bf16 v[8:11], v[156:159], v[188:191], v[8:11]
	s_barrier
	s_setprio 0
	s_add_u32 s69, s69, 0x100
	s_addc_u32 s70, s70, 0
	s_add_u32 s44, s44, 0x100
	s_addc_u32 s45, s45, 0
	s_cmp_ge_u32 s71, s67
	s_mov_b32 s46, s71
	s_cbranch_scc1 .Lpeel_done_2

.LBB0_2288:
	s_ashr_i32 s25, s24, 31
	s_lshl_b64 s[86:87], s[24:25], 21
	v_readlane_b32 s88, v254, 52
	v_readlane_b32 s89, v254, 53
	s_add_u32 s5, s88, s86
	s_addc_u32 s25, s89, s87
	s_add_u32 s38, s5, s38
	s_addc_u32 s39, s25, s39
	s_and_b64 s[48:49], s[48:49], exec
	s_cselect_b32 s5, s39, s45
	s_cselect_b32 s25, s38, s44
	s_add_i32 s43, s84, -2
	s_add_u32 s85, s44, 0x100
	s_addc_u32 s86, s45, 0
	s_add_u32 s44, s46, 0x100080
	s_addc_u32 s45, s47, 0
	s_mov_b32 s46, 0
	ds_read_b128 v[148:151], v159
	ds_read_b128 v[164:167], v159 offset:1024
	ds_read_b128 v[168:171], v159 offset:2048
	ds_read_b128 v[172:175], v159 offset:3072
	ds_read_b128 v[176:179], v160
	ds_read_b128 v[180:183], v160 offset:1024
	ds_read_b128 v[184:187], v160 offset:2048
	ds_read_b128 v[188:191], v160 offset:3072
	s_add_i32 s87, s46, 2
	s_add_u32 s47, s44, 0xfff00080
	s_addc_u32 s48, s45, -1
	s_cmp_eq_u32 s43, s46
	s_cselect_b32 s46, s25, s85
	s_cselect_b32 s49, s37, s48
	s_cselect_b32 s48, s36, s47
	s_cselect_b32 s47, s5, s86
	s_add_i32 m0, s94, 0xc000
	ds_read_b128 v[192:195], v161
	ds_read_b128 v[196:199], v161 offset:1024
	ds_read_b128 v[200:203], v161 offset:2048
	ds_read_b128 v[204:207], v161 offset:3072
	ds_read_b128 v[208:211], v161 offset:4096
	ds_read_b128 v[212:215], v161 offset:5120
	ds_read_b128 v[216:219], v161 offset:6144
	ds_read_b128 v[220:223], v161 offset:7168
	global_load_lds_dwordx4 v142, s[44:45]
	s_add_i32 m0, s94, 0xe000
	s_nop 0
	global_load_lds_dwordx4 v144, s[44:45]
	s_waitcnt vmcnt(24)
	s_waitcnt lgkmcnt(0)
	s_setprio 1
	s_barrier
	v_mfma_f32_16x16x32_bf16 v[112:115], v[148:151], v[192:195], 0
	v_mfma_f32_16x16x32_bf16 v[116:119], v[168:171], v[192:195], 0
	v_mfma_f32_16x16x32_bf16 v[100:103], v[148:151], v[200:203], 0
	v_mfma_f32_16x16x32_bf16 v[96:99], v[168:171], v[200:203], 0
	v_mfma_f32_16x16x32_bf16 v[84:87], v[148:151], v[208:211], 0
	v_mfma_f32_16x16x32_bf16 v[80:83], v[168:171], v[208:211], 0
	v_mfma_f32_16x16x32_bf16 v[52:55], v[148:151], v[216:219], 0
	v_mfma_f32_16x16x32_bf16 v[48:51], v[168:171], v[216:219], 0
	v_mfma_f32_16x16x32_bf16 v[112:115], v[164:167], v[196:199], v[112:115]
	v_mfma_f32_16x16x32_bf16 v[116:119], v[172:175], v[196:199], v[116:119]
	v_mfma_f32_16x16x32_bf16 v[100:103], v[164:167], v[204:207], v[100:103]
	v_mfma_f32_16x16x32_bf16 v[96:99], v[172:175], v[204:207], v[96:99]
	v_mfma_f32_16x16x32_bf16 v[84:87], v[164:167], v[212:215], v[84:87]
	v_mfma_f32_16x16x32_bf16 v[80:83], v[172:175], v[212:215], v[80:83]
	v_mfma_f32_16x16x32_bf16 v[52:55], v[164:167], v[220:223], v[52:55]
	v_mfma_f32_16x16x32_bf16 v[48:51], v[172:175], v[220:223], v[48:51]
	s_setprio 0
	s_setprio 1
	v_mfma_f32_16x16x32_bf16 v[124:127], v[176:179], v[192:195], 0
	v_mfma_f32_16x16x32_bf16 v[120:123], v[184:187], v[192:195], 0
	v_mfma_f32_16x16x32_bf16 v[108:111], v[176:179], v[200:203], 0
	v_mfma_f32_16x16x32_bf16 v[104:107], v[184:187], v[200:203], 0
	v_mfma_f32_16x16x32_bf16 v[92:95], v[176:179], v[208:211], 0
	v_mfma_f32_16x16x32_bf16 v[88:91], v[184:187], v[208:211], 0
	v_mfma_f32_16x16x32_bf16 v[68:71], v[176:179], v[216:219], 0
	v_mfma_f32_16x16x32_bf16 v[64:67], v[184:187], v[216:219], 0
	v_mfma_f32_16x16x32_bf16 v[124:127], v[180:183], v[196:199], v[124:127]
	v_mfma_f32_16x16x32_bf16 v[120:123], v[188:191], v[196:199], v[120:123]
	v_mfma_f32_16x16x32_bf16 v[108:111], v[180:183], v[204:207], v[108:111]
	v_mfma_f32_16x16x32_bf16 v[104:107], v[188:191], v[204:207], v[104:107]
	v_mfma_f32_16x16x32_bf16 v[92:95], v[180:183], v[212:215], v[92:95]
	v_mfma_f32_16x16x32_bf16 v[88:91], v[188:191], v[212:215], v[88:91]
	v_mfma_f32_16x16x32_bf16 v[68:71], v[180:183], v[220:223], v[68:71]
	v_mfma_f32_16x16x32_bf16 v[64:67], v[188:191], v[220:223], v[64:67]
	s_barrier
	s_setprio 0
	s_add_i32 s88, s77, s97
	s_add_u32 s98, s46, 0x80
	s_addc_u32 s99, s47, 0
	s_mov_b32 m0, s88
	ds_read_b128 v[192:195], v161 offset:16384
	ds_read_b128 v[196:199], v161 offset:17408
	ds_read_b128 v[200:203], v161 offset:18432
	ds_read_b128 v[204:207], v161 offset:19456
	ds_read_b128 v[208:211], v161 offset:20480
	ds_read_b128 v[212:215], v161 offset:21504
	ds_read_b128 v[216:219], v161 offset:22528
	ds_read_b128 v[220:223], v161 offset:23552
	global_load_lds_dwordx4 v132, s[46:47]
	s_add_i32 m0, s88, 0x2000
	s_add_u32 s88, s46, 0x100000
	s_addc_u32 s89, s47, 0
	s_add_i32 s90, s78, s97
	global_load_lds_dwordx4 v136, s[46:47]
	s_mov_b32 m0, s90
	s_add_u32 s100, s48, 0x80
	s_addc_u32 s101, s49, 0
	global_load_lds_dwordx4 v132, s[88:89]
	s_add_i32 m0, s90, 0x2000
	s_nop 0
	global_load_lds_dwordx4 v136, s[88:89]
	s_mov_b32 m0, s94
	s_nop 0
	global_load_lds_dwordx4 v130, s[48:49]
	s_mov_b32 m0, s52
	s_nop 0
	global_load_lds_dwordx4 v134, s[48:49]
	s_waitcnt vmcnt(8)
	s_waitcnt lgkmcnt(0)
	s_setprio 1
	s_barrier
	v_mfma_f32_16x16x32_bf16 v[60:63], v[148:151], v[192:195], 0
	v_mfma_f32_16x16x32_bf16 v[56:59], v[168:171], v[192:195], 0
	v_mfma_f32_16x16x32_bf16 v[36:39], v[148:151], v[200:203], 0
	v_mfma_f32_16x16x32_bf16 v[32:35], v[168:171], v[200:203], 0
	v_mfma_f32_16x16x32_bf16 v[20:23], v[148:151], v[208:211], 0
	v_mfma_f32_16x16x32_bf16 v[16:19], v[168:171], v[208:211], 0
	v_mfma_f32_16x16x32_bf16 v[4:7], v[148:151], v[216:219], 0
	v_mfma_f32_16x16x32_bf16 v[0:3], v[168:171], v[216:219], 0
	v_mfma_f32_16x16x32_bf16 v[60:63], v[164:167], v[196:199], v[60:63]
	v_mfma_f32_16x16x32_bf16 v[56:59], v[172:175], v[196:199], v[56:59]
	v_mfma_f32_16x16x32_bf16 v[36:39], v[164:167], v[204:207], v[36:39]
	v_mfma_f32_16x16x32_bf16 v[32:35], v[172:175], v[204:207], v[32:35]
	v_mfma_f32_16x16x32_bf16 v[20:23], v[164:167], v[212:215], v[20:23]
	v_mfma_f32_16x16x32_bf16 v[16:19], v[172:175], v[212:215], v[16:19]
	v_mfma_f32_16x16x32_bf16 v[4:7], v[164:167], v[220:223], v[4:7]
	v_mfma_f32_16x16x32_bf16 v[0:3], v[172:175], v[220:223], v[0:3]
	s_setprio 0
	s_setprio 1
	v_mfma_f32_16x16x32_bf16 v[76:79], v[176:179], v[192:195], 0
	v_mfma_f32_16x16x32_bf16 v[72:75], v[184:187], v[192:195], 0
	v_mfma_f32_16x16x32_bf16 v[44:47], v[176:179], v[200:203], 0
	v_mfma_f32_16x16x32_bf16 v[40:43], v[184:187], v[200:203], 0
	v_mfma_f32_16x16x32_bf16 v[28:31], v[176:179], v[208:211], 0
	v_mfma_f32_16x16x32_bf16 v[24:27], v[184:187], v[208:211], 0
	v_mfma_f32_16x16x32_bf16 v[12:15], v[176:179], v[216:219], 0
	v_mfma_f32_16x16x32_bf16 v[8:11], v[184:187], v[216:219], 0
	v_mfma_f32_16x16x32_bf16 v[76:79], v[180:183], v[196:199], v[76:79]
	v_mfma_f32_16x16x32_bf16 v[72:75], v[188:191], v[196:199], v[72:75]
	v_mfma_f32_16x16x32_bf16 v[44:47], v[180:183], v[204:207], v[44:47]
	v_mfma_f32_16x16x32_bf16 v[40:43], v[188:191], v[204:207], v[40:43]
	v_mfma_f32_16x16x32_bf16 v[28:31], v[180:183], v[212:215], v[28:31]
	v_mfma_f32_16x16x32_bf16 v[24:27], v[188:191], v[212:215], v[24:27]
	v_mfma_f32_16x16x32_bf16 v[12:15], v[180:183], v[220:223], v[12:15]
	v_mfma_f32_16x16x32_bf16 v[8:11], v[188:191], v[220:223], v[8:11]
	s_barrier
	s_setprio 0
	s_add_i32 s88, 0, 0x18000
	v_add_u32_e32 v163, s88, v157
	s_add_i32 s89, 0, 0x1c000
	ds_read_b128 v[148:151], v163
	ds_read_b128 v[164:167], v163 offset:1024
	ds_read_b128 v[168:171], v163 offset:2048
	ds_read_b128 v[172:175], v163 offset:3072
	v_add_u32_e32 v163, s89, v157
	ds_read_b128 v[176:179], v163
	ds_read_b128 v[180:183], v163 offset:1024
	ds_read_b128 v[184:187], v163 offset:2048
	ds_read_b128 v[188:191], v163 offset:3072
	s_add_u32 s48, s48, 0x100000
	s_addc_u32 s49, s49, 0
	s_mov_b32 m0, s53
	ds_read_b128 v[192:195], v161 offset:32768
	ds_read_b128 v[196:199], v161 offset:33792
	ds_read_b128 v[200:203], v161 offset:34816
	ds_read_b128 v[204:207], v161 offset:35840
	ds_read_b128 v[208:211], v161 offset:36864
	ds_read_b128 v[212:215], v161 offset:37888
	ds_read_b128 v[216:219], v161 offset:38912
	ds_read_b128 v[220:223], v161 offset:39936
	global_load_lds_dwordx4 v130, s[48:49]
	s_mov_b32 m0, s54
	s_nop 0
	global_load_lds_dwordx4 v134, s[48:49]
	s_waitcnt vmcnt(8)
	s_waitcnt lgkmcnt(0)
	s_setprio 1
	s_barrier
	v_mfma_f32_16x16x32_bf16 v[112:115], v[148:151], v[192:195], v[112:115]
	v_mfma_f32_16x16x32_bf16 v[116:119], v[168:171], v[192:195], v[116:119]
	v_mfma_f32_16x16x32_bf16 v[100:103], v[148:151], v[200:203], v[100:103]
	v_mfma_f32_16x16x32_bf16 v[96:99], v[168:171], v[200:203], v[96:99]
	v_mfma_f32_16x16x32_bf16 v[84:87], v[148:151], v[208:211], v[84:87]
	v_mfma_f32_16x16x32_bf16 v[80:83], v[168:171], v[208:211], v[80:83]
	v_mfma_f32_16x16x32_bf16 v[52:55], v[148:151], v[216:219], v[52:55]
	v_mfma_f32_16x16x32_bf16 v[48:51], v[168:171], v[216:219], v[48:51]
	v_mfma_f32_16x16x32_bf16 v[112:115], v[164:167], v[196:199], v[112:115]
	v_mfma_f32_16x16x32_bf16 v[116:119], v[172:175], v[196:199], v[116:119]
	v_mfma_f32_16x16x32_bf16 v[100:103], v[164:167], v[204:207], v[100:103]
	v_mfma_f32_16x16x32_bf16 v[96:99], v[172:175], v[204:207], v[96:99]
	v_mfma_f32_16x16x32_bf16 v[84:87], v[164:167], v[212:215], v[84:87]
	v_mfma_f32_16x16x32_bf16 v[80:83], v[172:175], v[212:215], v[80:83]
	v_mfma_f32_16x16x32_bf16 v[52:55], v[164:167], v[220:223], v[52:55]
	v_mfma_f32_16x16x32_bf16 v[48:51], v[172:175], v[220:223], v[48:51]
	s_setprio 0
	s_setprio 1
	v_mfma_f32_16x16x32_bf16 v[124:127], v[176:179], v[192:195], v[124:127]
	v_mfma_f32_16x16x32_bf16 v[120:123], v[184:187], v[192:195], v[120:123]
	v_mfma_f32_16x16x32_bf16 v[108:111], v[176:179], v[200:203], v[108:111]
	v_mfma_f32_16x16x32_bf16 v[104:107], v[184:187], v[200:203], v[104:107]
	v_mfma_f32_16x16x32_bf16 v[92:95], v[176:179], v[208:211], v[92:95]
	v_mfma_f32_16x16x32_bf16 v[88:91], v[184:187], v[208:211], v[88:91]
	v_mfma_f32_16x16x32_bf16 v[68:71], v[176:179], v[216:219], v[68:71]
	v_mfma_f32_16x16x32_bf16 v[64:67], v[184:187], v[216:219], v[64:67]
	v_mfma_f32_16x16x32_bf16 v[124:127], v[180:183], v[196:199], v[124:127]
	v_mfma_f32_16x16x32_bf16 v[120:123], v[188:191], v[196:199], v[120:123]
	v_mfma_f32_16x16x32_bf16 v[108:111], v[180:183], v[204:207], v[108:111]
	v_mfma_f32_16x16x32_bf16 v[104:107], v[188:191], v[204:207], v[104:107]
	v_mfma_f32_16x16x32_bf16 v[92:95], v[180:183], v[212:215], v[92:95]
	v_mfma_f32_16x16x32_bf16 v[88:91], v[188:191], v[212:215], v[88:91]
	v_mfma_f32_16x16x32_bf16 v[68:71], v[180:183], v[220:223], v[68:71]
	v_mfma_f32_16x16x32_bf16 v[64:67], v[188:191], v[220:223], v[64:67]
	s_barrier
	s_setprio 0
	s_add_i32 s48, s88, s97
	s_mov_b32 m0, s48
	ds_read_b128 v[192:195], v161 offset:49152
	ds_read_b128 v[196:199], v161 offset:50176
	ds_read_b128 v[200:203], v161 offset:51200
	ds_read_b128 v[204:207], v161 offset:52224
	ds_read_b128 v[208:211], v161 offset:53248
	ds_read_b128 v[212:215], v161 offset:54272
	ds_read_b128 v[216:219], v161 offset:55296
	ds_read_b128 v[220:223], v161 offset:56320
	global_load_lds_dwordx4 v132, s[98:99]
	s_add_i32 m0, s48, 0x2000
	s_add_u32 s46, s46, 0x100080
	s_addc_u32 s47, s47, 0
	s_add_i32 s48, s89, s97
	global_load_lds_dwordx4 v136, s[98:99]
	s_mov_b32 m0, s48
	s_nop 0
	global_load_lds_dwordx4 v132, s[46:47]
	s_add_i32 m0, s48, 0x2000
	s_nop 0
	global_load_lds_dwordx4 v136, s[46:47]
	s_mov_b32 m0, s68
	s_nop 0
	global_load_lds_dwordx4 v130, s[100:101]
	s_mov_b32 m0, s69
	s_nop 0
	global_load_lds_dwordx4 v134, s[100:101]
	s_waitcnt vmcnt(8)
	s_waitcnt lgkmcnt(0)
	s_setprio 1
	s_barrier
	v_mfma_f32_16x16x32_bf16 v[60:63], v[148:151], v[192:195], v[60:63]
	v_mfma_f32_16x16x32_bf16 v[56:59], v[168:171], v[192:195], v[56:59]
	v_mfma_f32_16x16x32_bf16 v[36:39], v[148:151], v[200:203], v[36:39]
	v_mfma_f32_16x16x32_bf16 v[32:35], v[168:171], v[200:203], v[32:35]
	v_mfma_f32_16x16x32_bf16 v[20:23], v[148:151], v[208:211], v[20:23]
	v_mfma_f32_16x16x32_bf16 v[16:19], v[168:171], v[208:211], v[16:19]
	v_mfma_f32_16x16x32_bf16 v[4:7], v[148:151], v[216:219], v[4:7]
	v_mfma_f32_16x16x32_bf16 v[0:3], v[168:171], v[216:219], v[0:3]
	v_mfma_f32_16x16x32_bf16 v[60:63], v[164:167], v[196:199], v[60:63]
	v_mfma_f32_16x16x32_bf16 v[56:59], v[172:175], v[196:199], v[56:59]
	v_mfma_f32_16x16x32_bf16 v[36:39], v[164:167], v[204:207], v[36:39]
	v_mfma_f32_16x16x32_bf16 v[32:35], v[172:175], v[204:207], v[32:35]
	v_mfma_f32_16x16x32_bf16 v[20:23], v[164:167], v[212:215], v[20:23]
	v_mfma_f32_16x16x32_bf16 v[16:19], v[172:175], v[212:215], v[16:19]
	v_mfma_f32_16x16x32_bf16 v[4:7], v[164:167], v[220:223], v[4:7]
	v_mfma_f32_16x16x32_bf16 v[0:3], v[172:175], v[220:223], v[0:3]
	s_setprio 0
	s_setprio 1
	v_mfma_f32_16x16x32_bf16 v[76:79], v[176:179], v[192:195], v[76:79]
	v_mfma_f32_16x16x32_bf16 v[72:75], v[184:187], v[192:195], v[72:75]
	v_mfma_f32_16x16x32_bf16 v[44:47], v[176:179], v[200:203], v[44:47]
	v_mfma_f32_16x16x32_bf16 v[40:43], v[184:187], v[200:203], v[40:43]
	v_mfma_f32_16x16x32_bf16 v[28:31], v[176:179], v[208:211], v[28:31]
	v_mfma_f32_16x16x32_bf16 v[24:27], v[184:187], v[208:211], v[24:27]
	v_mfma_f32_16x16x32_bf16 v[12:15], v[176:179], v[216:219], v[12:15]
	v_mfma_f32_16x16x32_bf16 v[8:11], v[184:187], v[216:219], v[8:11]
	v_mfma_f32_16x16x32_bf16 v[76:79], v[180:183], v[196:199], v[76:79]
	v_mfma_f32_16x16x32_bf16 v[72:75], v[188:191], v[196:199], v[72:75]
	v_mfma_f32_16x16x32_bf16 v[44:47], v[180:183], v[204:207], v[44:47]
	v_mfma_f32_16x16x32_bf16 v[40:43], v[188:191], v[204:207], v[40:43]
	v_mfma_f32_16x16x32_bf16 v[28:31], v[180:183], v[212:215], v[28:31]
	v_mfma_f32_16x16x32_bf16 v[24:27], v[188:191], v[212:215], v[24:27]
	v_mfma_f32_16x16x32_bf16 v[12:15], v[180:183], v[220:223], v[12:15]
	v_mfma_f32_16x16x32_bf16 v[8:11], v[188:191], v[220:223], v[8:11]
	s_barrier
	s_setprio 0
	s_add_u32 s85, s85, 0x100
	s_addc_u32 s86, s86, 0
	s_add_u32 s44, s44, 0x100
	s_addc_u32 s45, s45, 0
	s_cmp_ge_u32 s87, s84
	s_mov_b32 s46, s87
	s_cbranch_scc1 .Lpeel_done_3

.LBB0_2452:
	s_cmp_lt_u32 s35, 0x3fffffff
	s_cselect_b64 s[38:39], -1, 0
	s_ashr_i32 s35, s34, 31
	s_and_b64 s[38:39], s[4:5], s[38:39]
	s_lshl_b64 s[4:5], s[34:35], 23
	s_add_u32 s4, s2, s4
	s_addc_u32 s5, s3, s5
	s_add_u32 s4, s4, s36
	s_addc_u32 s5, s5, s37
	s_and_b64 s[48:49], s[38:39], exec
	s_cselect_b32 s35, s5, s47
	s_cselect_b32 s41, s4, s46
	s_ashr_i32 s31, s30, 31
	s_lshl_b64 s[48:49], s[30:31], 23
	v_readlane_b32 s78, v254, 54
	v_readlane_b32 s79, v254, 55
	s_add_u32 s31, s78, s48
	s_addc_u32 s43, s79, s49
	s_add_u32 s36, s31, s36
	s_addc_u32 s37, s43, s37
	s_and_b64 s[48:49], s[38:39], exec
	s_cselect_b32 s31, s37, s45
	s_cselect_b32 s43, s36, s44
	s_add_i32 s75, s76, -2
	s_add_u32 s77, s44, 0x100
	s_addc_u32 s78, s45, 0
	s_add_u32 s44, s46, 0x400080
	s_addc_u32 s45, s47, 0
	s_mov_b32 s46, 0
	ds_read_b128 v[128:131], v228
	ds_read_b128 v[132:135], v228 offset:1024
	ds_read_b128 v[136:139], v228 offset:2048
	ds_read_b128 v[140:143], v228 offset:3072
	ds_read_b128 v[144:147], v229
	ds_read_b128 v[148:151], v229 offset:1024
	ds_read_b128 v[152:155], v229 offset:2048
	ds_read_b128 v[156:159], v229 offset:3072
	s_add_i32 s79, s46, 2
	s_add_u32 s47, s44, 0xffc00080
	s_addc_u32 s48, s45, -1
	s_cmp_eq_u32 s75, s46
	s_cselect_b32 s46, s43, s77
	s_cselect_b32 s49, s35, s48
	s_cselect_b32 s48, s41, s47
	s_cselect_b32 s47, s31, s78
	s_add_i32 m0, s94, 0xc000
	ds_read_b128 v[160:163], v230
	ds_read_b128 v[164:167], v230 offset:1024
	ds_read_b128 v[168:171], v230 offset:2048
	ds_read_b128 v[172:175], v230 offset:3072
	ds_read_b128 v[176:179], v230 offset:4096
	ds_read_b128 v[180:183], v230 offset:5120
	ds_read_b128 v[184:187], v230 offset:6144
	ds_read_b128 v[188:191], v230 offset:7168
	global_load_lds_dwordx4 v202, s[44:45]
	s_add_i32 m0, s94, 0xe000
	s_nop 0
	global_load_lds_dwordx4 v204, s[44:45]
	s_waitcnt vmcnt(24)
	s_waitcnt lgkmcnt(0)
	s_setprio 1
	s_barrier
	v_mfma_f32_16x16x32_bf16 v[112:115], v[128:131], v[160:163], 0
	v_mfma_f32_16x16x32_bf16 v[116:119], v[136:139], v[160:163], 0
	v_mfma_f32_16x16x32_bf16 v[100:103], v[128:131], v[168:171], 0
	v_mfma_f32_16x16x32_bf16 v[96:99], v[136:139], v[168:171], 0
	v_mfma_f32_16x16x32_bf16 v[84:87], v[128:131], v[176:179], 0
	v_mfma_f32_16x16x32_bf16 v[80:83], v[136:139], v[176:179], 0
	v_mfma_f32_16x16x32_bf16 v[52:55], v[128:131], v[184:187], 0
	v_mfma_f32_16x16x32_bf16 v[48:51], v[136:139], v[184:187], 0
	v_mfma_f32_16x16x32_bf16 v[112:115], v[132:135], v[164:167], v[112:115]
	v_mfma_f32_16x16x32_bf16 v[116:119], v[140:143], v[164:167], v[116:119]
	v_mfma_f32_16x16x32_bf16 v[100:103], v[132:135], v[172:175], v[100:103]
	v_mfma_f32_16x16x32_bf16 v[96:99], v[140:143], v[172:175], v[96:99]
	v_mfma_f32_16x16x32_bf16 v[84:87], v[132:135], v[180:183], v[84:87]
	v_mfma_f32_16x16x32_bf16 v[80:83], v[140:143], v[180:183], v[80:83]
	v_mfma_f32_16x16x32_bf16 v[52:55], v[132:135], v[188:191], v[52:55]
	v_mfma_f32_16x16x32_bf16 v[48:51], v[140:143], v[188:191], v[48:51]
	s_setprio 0
	s_setprio 1
	v_mfma_f32_16x16x32_bf16 v[124:127], v[144:147], v[160:163], 0
	v_mfma_f32_16x16x32_bf16 v[120:123], v[152:155], v[160:163], 0
	v_mfma_f32_16x16x32_bf16 v[108:111], v[144:147], v[168:171], 0
	v_mfma_f32_16x16x32_bf16 v[104:107], v[152:155], v[168:171], 0
	v_mfma_f32_16x16x32_bf16 v[92:95], v[144:147], v[176:179], 0
	v_mfma_f32_16x16x32_bf16 v[88:91], v[152:155], v[176:179], 0
	v_mfma_f32_16x16x32_bf16 v[68:71], v[144:147], v[184:187], 0
	v_mfma_f32_16x16x32_bf16 v[64:67], v[152:155], v[184:187], 0
	v_mfma_f32_16x16x32_bf16 v[124:127], v[148:151], v[164:167], v[124:127]
	v_mfma_f32_16x16x32_bf16 v[120:123], v[156:159], v[164:167], v[120:123]
	v_mfma_f32_16x16x32_bf16 v[108:111], v[148:151], v[172:175], v[108:111]
	v_mfma_f32_16x16x32_bf16 v[104:107], v[156:159], v[172:175], v[104:107]
	v_mfma_f32_16x16x32_bf16 v[92:95], v[148:151], v[180:183], v[92:95]
	v_mfma_f32_16x16x32_bf16 v[88:91], v[156:159], v[180:183], v[88:91]
	v_mfma_f32_16x16x32_bf16 v[68:71], v[148:151], v[188:191], v[68:71]
	v_mfma_f32_16x16x32_bf16 v[64:67], v[156:159], v[188:191], v[64:67]
	s_barrier
	s_setprio 0
	s_add_i32 s80, s68, s97
	s_add_u32 s98, s46, 0x80
	s_addc_u32 s99, s47, 0
	s_mov_b32 m0, s80
	ds_read_b128 v[160:163], v230 offset:16384
	ds_read_b128 v[164:167], v230 offset:17408
	ds_read_b128 v[168:171], v230 offset:18432
	ds_read_b128 v[172:175], v230 offset:19456
	ds_read_b128 v[176:179], v230 offset:20480
	ds_read_b128 v[180:183], v230 offset:21504
	ds_read_b128 v[184:187], v230 offset:22528
	ds_read_b128 v[188:191], v230 offset:23552
	global_load_lds_dwordx4 v194, s[46:47]
	s_add_i32 m0, s80, 0x2000
	s_add_u32 s80, s46, 0x400000
	s_addc_u32 s81, s47, 0
	s_add_i32 s84, s69, s97
	global_load_lds_dwordx4 v198, s[46:47]
	s_mov_b32 m0, s84
	s_add_u32 s100, s48, 0x80
	s_addc_u32 s101, s49, 0
	global_load_lds_dwordx4 v194, s[80:81]
	s_add_i32 m0, s84, 0x2000
	s_nop 0
	global_load_lds_dwordx4 v198, s[80:81]
	s_mov_b32 m0, s94
	s_nop 0
	global_load_lds_dwordx4 v192, s[48:49]
	s_mov_b32 m0, s51
	s_nop 0
	global_load_lds_dwordx4 v196, s[48:49]
	s_waitcnt vmcnt(8)
	s_waitcnt lgkmcnt(0)
	s_setprio 1
	s_barrier
	v_mfma_f32_16x16x32_bf16 v[60:63], v[128:131], v[160:163], 0
	v_mfma_f32_16x16x32_bf16 v[56:59], v[136:139], v[160:163], 0
	v_mfma_f32_16x16x32_bf16 v[36:39], v[128:131], v[168:171], 0
	v_mfma_f32_16x16x32_bf16 v[32:35], v[136:139], v[168:171], 0
	v_mfma_f32_16x16x32_bf16 v[20:23], v[128:131], v[176:179], 0
	v_mfma_f32_16x16x32_bf16 v[16:19], v[136:139], v[176:179], 0
	v_mfma_f32_16x16x32_bf16 v[4:7], v[128:131], v[184:187], 0
	v_mfma_f32_16x16x32_bf16 v[0:3], v[136:139], v[184:187], 0
	v_mfma_f32_16x16x32_bf16 v[60:63], v[132:135], v[164:167], v[60:63]
	v_mfma_f32_16x16x32_bf16 v[56:59], v[140:143], v[164:167], v[56:59]
	v_mfma_f32_16x16x32_bf16 v[36:39], v[132:135], v[172:175], v[36:39]
	v_mfma_f32_16x16x32_bf16 v[32:35], v[140:143], v[172:175], v[32:35]
	v_mfma_f32_16x16x32_bf16 v[20:23], v[132:135], v[180:183], v[20:23]
	v_mfma_f32_16x16x32_bf16 v[16:19], v[140:143], v[180:183], v[16:19]
	v_mfma_f32_16x16x32_bf16 v[4:7], v[132:135], v[188:191], v[4:7]
	v_mfma_f32_16x16x32_bf16 v[0:3], v[140:143], v[188:191], v[0:3]
	s_setprio 0
	s_setprio 1
	v_mfma_f32_16x16x32_bf16 v[76:79], v[144:147], v[160:163], 0
	v_mfma_f32_16x16x32_bf16 v[72:75], v[152:155], v[160:163], 0
	v_mfma_f32_16x16x32_bf16 v[44:47], v[144:147], v[168:171], 0
	v_mfma_f32_16x16x32_bf16 v[40:43], v[152:155], v[168:171], 0
	v_mfma_f32_16x16x32_bf16 v[28:31], v[144:147], v[176:179], 0
	v_mfma_f32_16x16x32_bf16 v[24:27], v[152:155], v[176:179], 0
	v_mfma_f32_16x16x32_bf16 v[12:15], v[144:147], v[184:187], 0
	v_mfma_f32_16x16x32_bf16 v[8:11], v[152:155], v[184:187], 0
	v_mfma_f32_16x16x32_bf16 v[76:79], v[148:151], v[164:167], v[76:79]
	v_mfma_f32_16x16x32_bf16 v[72:75], v[156:159], v[164:167], v[72:75]
	v_mfma_f32_16x16x32_bf16 v[44:47], v[148:151], v[172:175], v[44:47]
	v_mfma_f32_16x16x32_bf16 v[40:43], v[156:159], v[172:175], v[40:43]
	v_mfma_f32_16x16x32_bf16 v[28:31], v[148:151], v[180:183], v[28:31]
	v_mfma_f32_16x16x32_bf16 v[24:27], v[156:159], v[180:183], v[24:27]
	v_mfma_f32_16x16x32_bf16 v[12:15], v[148:151], v[188:191], v[12:15]
	v_mfma_f32_16x16x32_bf16 v[8:11], v[156:159], v[188:191], v[8:11]
	s_barrier
	s_setprio 0
	s_add_i32 s80, 0, 0x18000
	s_add_i32 s81, 0, 0x1c000
	v_add_u32_e32 v140, s80, v226
	v_add_u32_e32 v156, s81, v226
	ds_read_b128 v[128:131], v140
	ds_read_b128 v[132:135], v140 offset:1024
	ds_read_b128 v[136:139], v140 offset:2048
	ds_read_b128 v[140:143], v140 offset:3072
	ds_read_b128 v[144:147], v156
	ds_read_b128 v[148:151], v156 offset:1024
	ds_read_b128 v[152:155], v156 offset:2048
	ds_read_b128 v[156:159], v156 offset:3072
	s_add_u32 s48, s48, 0x400000
	s_addc_u32 s49, s49, 0
	s_mov_b32 m0, s52
	ds_read_b128 v[160:163], v230 offset:32768
	ds_read_b128 v[164:167], v230 offset:33792
	ds_read_b128 v[168:171], v230 offset:34816
	ds_read_b128 v[172:175], v230 offset:35840
	ds_read_b128 v[176:179], v230 offset:36864
	ds_read_b128 v[180:183], v230 offset:37888
	ds_read_b128 v[184:187], v230 offset:38912
	ds_read_b128 v[188:191], v230 offset:39936
	global_load_lds_dwordx4 v192, s[48:49]
	s_mov_b32 m0, s53
	s_nop 0
	global_load_lds_dwordx4 v196, s[48:49]
	s_waitcnt vmcnt(8)
	s_waitcnt lgkmcnt(0)
	s_setprio 1
	s_barrier
	v_mfma_f32_16x16x32_bf16 v[112:115], v[128:131], v[160:163], v[112:115]
	v_mfma_f32_16x16x32_bf16 v[116:119], v[136:139], v[160:163], v[116:119]
	v_mfma_f32_16x16x32_bf16 v[100:103], v[128:131], v[168:171], v[100:103]
	v_mfma_f32_16x16x32_bf16 v[96:99], v[136:139], v[168:171], v[96:99]
	v_mfma_f32_16x16x32_bf16 v[84:87], v[128:131], v[176:179], v[84:87]
	v_mfma_f32_16x16x32_bf16 v[80:83], v[136:139], v[176:179], v[80:83]
	v_mfma_f32_16x16x32_bf16 v[52:55], v[128:131], v[184:187], v[52:55]
	v_mfma_f32_16x16x32_bf16 v[48:51], v[136:139], v[184:187], v[48:51]
	v_mfma_f32_16x16x32_bf16 v[112:115], v[132:135], v[164:167], v[112:115]
	v_mfma_f32_16x16x32_bf16 v[116:119], v[140:143], v[164:167], v[116:119]
	v_mfma_f32_16x16x32_bf16 v[100:103], v[132:135], v[172:175], v[100:103]
	v_mfma_f32_16x16x32_bf16 v[96:99], v[140:143], v[172:175], v[96:99]
	v_mfma_f32_16x16x32_bf16 v[84:87], v[132:135], v[180:183], v[84:87]
	v_mfma_f32_16x16x32_bf16 v[80:83], v[140:143], v[180:183], v[80:83]
	v_mfma_f32_16x16x32_bf16 v[52:55], v[132:135], v[188:191], v[52:55]
	v_mfma_f32_16x16x32_bf16 v[48:51], v[140:143], v[188:191], v[48:51]
	s_setprio 0
	s_setprio 1
	v_mfma_f32_16x16x32_bf16 v[124:127], v[144:147], v[160:163], v[124:127]
	v_mfma_f32_16x16x32_bf16 v[120:123], v[152:155], v[160:163], v[120:123]
	v_mfma_f32_16x16x32_bf16 v[108:111], v[144:147], v[168:171], v[108:111]
	v_mfma_f32_16x16x32_bf16 v[104:107], v[152:155], v[168:171], v[104:107]
	v_mfma_f32_16x16x32_bf16 v[92:95], v[144:147], v[176:179], v[92:95]
	v_mfma_f32_16x16x32_bf16 v[88:91], v[152:155], v[176:179], v[88:91]
	v_mfma_f32_16x16x32_bf16 v[68:71], v[144:147], v[184:187], v[68:71]
	v_mfma_f32_16x16x32_bf16 v[64:67], v[152:155], v[184:187], v[64:67]
	v_mfma_f32_16x16x32_bf16 v[124:127], v[148:151], v[164:167], v[124:127]
	v_mfma_f32_16x16x32_bf16 v[120:123], v[156:159], v[164:167], v[120:123]
	v_mfma_f32_16x16x32_bf16 v[108:111], v[148:151], v[172:175], v[108:111]
	v_mfma_f32_16x16x32_bf16 v[104:107], v[156:159], v[172:175], v[104:107]
	v_mfma_f32_16x16x32_bf16 v[92:95], v[148:151], v[180:183], v[92:95]
	v_mfma_f32_16x16x32_bf16 v[88:91], v[156:159], v[180:183], v[88:91]
	v_mfma_f32_16x16x32_bf16 v[68:71], v[148:151], v[188:191], v[68:71]
	v_mfma_f32_16x16x32_bf16 v[64:67], v[156:159], v[188:191], v[64:67]
	s_barrier
	s_setprio 0
	s_add_i32 s48, s80, s97
	s_mov_b32 m0, s48
	ds_read_b128 v[160:163], v230 offset:49152
	ds_read_b128 v[164:167], v230 offset:50176
	ds_read_b128 v[168:171], v230 offset:51200
	ds_read_b128 v[172:175], v230 offset:52224
	ds_read_b128 v[176:179], v230 offset:53248
	ds_read_b128 v[180:183], v230 offset:54272
	ds_read_b128 v[184:187], v230 offset:55296
	ds_read_b128 v[188:191], v230 offset:56320
	global_load_lds_dwordx4 v194, s[98:99]
	s_add_i32 m0, s48, 0x2000
	s_add_u32 s46, s46, 0x400080
	s_addc_u32 s47, s47, 0
	s_add_i32 s48, s81, s97
	global_load_lds_dwordx4 v198, s[98:99]
	s_mov_b32 m0, s48
	s_nop 0
	global_load_lds_dwordx4 v194, s[46:47]
	s_add_i32 m0, s48, 0x2000
	s_nop 0
	global_load_lds_dwordx4 v198, s[46:47]
	s_mov_b32 m0, s54
	s_nop 0
	global_load_lds_dwordx4 v192, s[100:101]
	s_mov_b32 m0, s55
	s_nop 0
	global_load_lds_dwordx4 v196, s[100:101]
	s_waitcnt vmcnt(8)
	s_waitcnt lgkmcnt(0)
	s_setprio 1
	s_barrier
	v_mfma_f32_16x16x32_bf16 v[60:63], v[128:131], v[160:163], v[60:63]
	v_mfma_f32_16x16x32_bf16 v[56:59], v[136:139], v[160:163], v[56:59]
	v_mfma_f32_16x16x32_bf16 v[36:39], v[128:131], v[168:171], v[36:39]
	v_mfma_f32_16x16x32_bf16 v[32:35], v[136:139], v[168:171], v[32:35]
	v_mfma_f32_16x16x32_bf16 v[20:23], v[128:131], v[176:179], v[20:23]
	v_mfma_f32_16x16x32_bf16 v[16:19], v[136:139], v[176:179], v[16:19]
	v_mfma_f32_16x16x32_bf16 v[4:7], v[128:131], v[184:187], v[4:7]
	v_mfma_f32_16x16x32_bf16 v[0:3], v[136:139], v[184:187], v[0:3]
	v_mfma_f32_16x16x32_bf16 v[60:63], v[132:135], v[164:167], v[60:63]
	v_mfma_f32_16x16x32_bf16 v[56:59], v[140:143], v[164:167], v[56:59]
	v_mfma_f32_16x16x32_bf16 v[36:39], v[132:135], v[172:175], v[36:39]
	v_mfma_f32_16x16x32_bf16 v[32:35], v[140:143], v[172:175], v[32:35]
	v_mfma_f32_16x16x32_bf16 v[20:23], v[132:135], v[180:183], v[20:23]
	v_mfma_f32_16x16x32_bf16 v[16:19], v[140:143], v[180:183], v[16:19]
	v_mfma_f32_16x16x32_bf16 v[4:7], v[132:135], v[188:191], v[4:7]
	v_mfma_f32_16x16x32_bf16 v[0:3], v[140:143], v[188:191], v[0:3]
	s_setprio 0
	s_setprio 1
	v_mfma_f32_16x16x32_bf16 v[76:79], v[144:147], v[160:163], v[76:79]
	v_mfma_f32_16x16x32_bf16 v[72:75], v[152:155], v[160:163], v[72:75]
	v_mfma_f32_16x16x32_bf16 v[44:47], v[144:147], v[168:171], v[44:47]
	v_mfma_f32_16x16x32_bf16 v[40:43], v[152:155], v[168:171], v[40:43]
	v_mfma_f32_16x16x32_bf16 v[28:31], v[144:147], v[176:179], v[28:31]
	v_mfma_f32_16x16x32_bf16 v[24:27], v[152:155], v[176:179], v[24:27]
	v_mfma_f32_16x16x32_bf16 v[12:15], v[144:147], v[184:187], v[12:15]
	v_mfma_f32_16x16x32_bf16 v[8:11], v[152:155], v[184:187], v[8:11]
	v_mfma_f32_16x16x32_bf16 v[76:79], v[148:151], v[164:167], v[76:79]
	v_mfma_f32_16x16x32_bf16 v[72:75], v[156:159], v[164:167], v[72:75]
	v_mfma_f32_16x16x32_bf16 v[44:47], v[148:151], v[172:175], v[44:47]
	v_mfma_f32_16x16x32_bf16 v[40:43], v[156:159], v[172:175], v[40:43]
	v_mfma_f32_16x16x32_bf16 v[28:31], v[148:151], v[180:183], v[28:31]
	v_mfma_f32_16x16x32_bf16 v[24:27], v[156:159], v[180:183], v[24:27]
	v_mfma_f32_16x16x32_bf16 v[12:15], v[148:151], v[188:191], v[12:15]
	v_mfma_f32_16x16x32_bf16 v[8:11], v[156:159], v[188:191], v[8:11]
	s_barrier
	s_setprio 0
	s_add_u32 s77, s77, 0x100
	s_addc_u32 s78, s78, 0
	s_add_u32 s44, s44, 0x100
	s_addc_u32 s45, s45, 0
	s_cmp_ge_u32 s79, s76
	s_mov_b32 s46, s79
	s_cbranch_scc1 .Lpeel_done_4
